# attention Q-tile staging loads batched; barrier waiters poll top generation directly; GEMM epilogue stores write-through (sc1); epilogue loads hoisted
# speedup vs baseline: 1.0246x; 1.0246x over previous
.LBB0_256:
	s_lshl_b32 s0, s1, 8
	s_cmp_lt_i32 s0, s85
	v_or_b32_e32 v143, s0, v149
	s_cselect_b64 s[0:1], -1, 0
	s_and_b64 s[8:9], s[0:1], exec
	s_cselect_b32 s8, 0, s84
	v_add_u32_e32 v152, s8, v143
	s_and_b64 s[0:1], s[6:7], s[0:1]
	s_and_b64 s[0:1], s[0:1], exec
	s_cselect_b32 s0, s97, s17
	s_cselect_b32 s1, s96, s16
	s_cselect_b32 s8, s91, 0x1000
	v_ashrrev_i32_e32 v153, 31, v152
	s_waitcnt vmcnt(7)
	v_ffbh_u32_e32 v143, v183
	v_min_u32_e32 v143, 32, v143
	v_lshlrev_b64 v[144:145], v143, v[182:183]
	v_min_u32_e32 v144, 1, v144
	v_or_b32_e32 v144, v145, v144
	v_cvt_f32_u32_e32 v151, v144
	v_sub_u32_e32 v143, 32, v143
	v_mov_b32_e32 v144, s1
	v_mov_b32_e32 v145, s0
	v_ldexp_f32 v143, v151, v143
	v_fmamk_f32 v143, v143, 0x2e000000, v211
	v_mul_f32_e32 v151, 0x4b800000, v143
	v_cmp_gt_f32_e32 vcc, s20, v143
	v_mad_i64_i32 v[154:155], s[0:1], s8, v142, 0
	s_nop 0
	v_cndmask_b32_e32 v143, v143, v151, vcc
	v_rsq_f32_e32 v143, v143
	v_lshl_add_u64 v[144:145], v[152:153], 1, v[144:145]
	v_lshl_add_u64 v[152:153], v[154:155], 1, v[144:145]
	v_mul_f32_e32 v151, 0x45800000, v143
	v_cndmask_b32_e32 v154, v143, v151, vcc
	v_pk_mul_f32 v[128:129], v[128:129], v[154:155] op_sel_hi:[1,0]
	v_pk_mul_f32 v[126:127], v[126:127], v[154:155] op_sel_hi:[1,0]
	v_pk_mul_f32 v[124:125], v[124:125], v[154:155] op_sel_hi:[1,0]
	v_pk_mul_f32 v[122:123], v[122:123], v[154:155] op_sel_hi:[1,0]
	v_pk_mul_f32 v[120:121], v[120:121], v[154:155] op_sel_hi:[1,0]
	v_pk_mul_f32 v[118:119], v[118:119], v[154:155] op_sel_hi:[1,0]
	v_pk_mul_f32 v[156:157], v[116:117], v[154:155] op_sel_hi:[1,0]
	v_pk_mul_f32 v[154:155], v[114:115], v[154:155] op_sel_hi:[1,0]
	v_cvt_pk_bf16_f32 v114, v126, v127
	v_cvt_pk_bf16_f32 v115, v128, v129
	v_cvt_pk_bf16_f32 v116, v122, v123
	v_cvt_pk_bf16_f32 v117, v124, v125
	global_store_dwordx4 v[152:153], v[114:117], off sc1
	s_nop 1
	v_cvt_pk_bf16_f32 v114, v118, v119
	v_cvt_pk_bf16_f32 v115, v120, v121
	v_cvt_pk_bf16_f32 v116, v154, v155
	v_cvt_pk_bf16_f32 v117, v156, v157
	global_store_dwordx4 v[152:153], v[114:117], off offset:256 sc1
	s_nop 0
	s_waitcnt vmcnt(8)
	v_ffbh_u32_e32 v116, v185
	v_min_u32_e32 v116, 32, v116
	v_lshlrev_b64 v[114:115], v116, v[184:185]
	v_min_u32_e32 v114, 1, v114
	v_or_b32_e32 v114, v115, v114
	v_cvt_f32_u32_e32 v114, v114
	v_sub_u32_e32 v116, 32, v116
	v_or_b32_e32 v115, 16, v142
	v_ldexp_f32 v114, v114, v116
	v_fmamk_f32 v114, v114, 0x2e000000, v211
	v_mul_f32_e32 v116, 0x4b800000, v114
	v_cmp_gt_f32_e32 vcc, s20, v114
	s_nop 1
	v_cndmask_b32_e32 v114, v114, v116, vcc
	v_rsq_f32_e32 v116, v114
	v_mad_i64_i32 v[114:115], s[0:1], s8, v115, 0
	v_lshl_add_u64 v[114:115], v[114:115], 1, v[144:145]
	v_mul_f32_e32 v117, 0x45800000, v116
	v_cndmask_b32_e32 v116, v116, v117, vcc
	v_pk_mul_f32 v[112:113], v[112:113], v[116:117] op_sel_hi:[1,0]
	v_pk_mul_f32 v[110:111], v[110:111], v[116:117] op_sel_hi:[1,0]
	v_pk_mul_f32 v[108:109], v[108:109], v[116:117] op_sel_hi:[1,0]
	v_pk_mul_f32 v[106:107], v[106:107], v[116:117] op_sel_hi:[1,0]
	v_pk_mul_f32 v[104:105], v[104:105], v[116:117] op_sel_hi:[1,0]
	v_pk_mul_f32 v[102:103], v[102:103], v[116:117] op_sel_hi:[1,0]
	v_pk_mul_f32 v[118:119], v[100:101], v[116:117] op_sel_hi:[1,0]
	v_pk_mul_f32 v[116:117], v[98:99], v[116:117] op_sel_hi:[1,0]
	v_cvt_pk_bf16_f32 v98, v110, v111
	v_cvt_pk_bf16_f32 v99, v112, v113
	v_cvt_pk_bf16_f32 v100, v106, v107
	v_cvt_pk_bf16_f32 v101, v108, v109
	global_store_dwordx4 v[114:115], v[98:101], off sc1
	s_nop 1
	v_cvt_pk_bf16_f32 v98, v102, v103
	v_cvt_pk_bf16_f32 v99, v104, v105
	v_cvt_pk_bf16_f32 v100, v116, v117
	v_cvt_pk_bf16_f32 v101, v118, v119
	global_store_dwordx4 v[114:115], v[98:101], off offset:256 sc1
	s_nop 0
	s_waitcnt vmcnt(9)
	v_ffbh_u32_e32 v100, v187
	v_min_u32_e32 v100, 32, v100
	v_lshlrev_b64 v[98:99], v100, v[186:187]
	v_min_u32_e32 v98, 1, v98
	v_or_b32_e32 v98, v99, v98
	v_cvt_f32_u32_e32 v98, v98
	v_sub_u32_e32 v100, 32, v100
	v_or_b32_e32 v99, 32, v142
	v_ldexp_f32 v98, v98, v100
	v_fmamk_f32 v98, v98, 0x2e000000, v211
	v_mul_f32_e32 v100, 0x4b800000, v98
	v_cmp_gt_f32_e32 vcc, s20, v98
	s_nop 1
	v_cndmask_b32_e32 v98, v98, v100, vcc
	v_rsq_f32_e32 v100, v98
	v_mad_i64_i32 v[98:99], s[0:1], s8, v99, 0
	v_lshl_add_u64 v[98:99], v[98:99], 1, v[144:145]
	v_mul_f32_e32 v101, 0x45800000, v100
	v_cndmask_b32_e32 v100, v100, v101, vcc
	v_pk_mul_f32 v[96:97], v[96:97], v[100:101] op_sel_hi:[1,0]
	v_pk_mul_f32 v[94:95], v[94:95], v[100:101] op_sel_hi:[1,0]
	v_pk_mul_f32 v[92:93], v[92:93], v[100:101] op_sel_hi:[1,0]
	v_pk_mul_f32 v[90:91], v[90:91], v[100:101] op_sel_hi:[1,0]
	v_pk_mul_f32 v[88:89], v[88:89], v[100:101] op_sel_hi:[1,0]
	v_pk_mul_f32 v[86:87], v[86:87], v[100:101] op_sel_hi:[1,0]
	v_pk_mul_f32 v[102:103], v[84:85], v[100:101] op_sel_hi:[1,0]
	v_pk_mul_f32 v[100:101], v[82:83], v[100:101] op_sel_hi:[1,0]
	v_cvt_pk_bf16_f32 v82, v94, v95
	v_cvt_pk_bf16_f32 v83, v96, v97
	v_cvt_pk_bf16_f32 v84, v90, v91
	v_cvt_pk_bf16_f32 v85, v92, v93
	global_store_dwordx4 v[98:99], v[82:85], off sc1
	s_nop 1
	v_cvt_pk_bf16_f32 v82, v86, v87
	v_cvt_pk_bf16_f32 v83, v88, v89
	v_cvt_pk_bf16_f32 v84, v100, v101
	v_cvt_pk_bf16_f32 v85, v102, v103
	global_store_dwordx4 v[98:99], v[82:85], off offset:256 sc1
	s_nop 0
	s_waitcnt vmcnt(10)
	v_ffbh_u32_e32 v84, v189
	v_min_u32_e32 v84, 32, v84
	v_lshlrev_b64 v[82:83], v84, v[188:189]
	v_min_u32_e32 v82, 1, v82
	v_or_b32_e32 v82, v83, v82
	v_cvt_f32_u32_e32 v82, v82
	v_sub_u32_e32 v84, 32, v84
	v_or_b32_e32 v83, 48, v142
	v_ldexp_f32 v82, v82, v84
	v_fmamk_f32 v82, v82, 0x2e000000, v211
	v_mul_f32_e32 v84, 0x4b800000, v82
	v_cmp_gt_f32_e32 vcc, s20, v82
	s_nop 1
	v_cndmask_b32_e32 v82, v82, v84, vcc
	v_rsq_f32_e32 v84, v82
	v_mad_i64_i32 v[82:83], s[0:1], s8, v83, 0
	v_lshl_add_u64 v[82:83], v[82:83], 1, v[144:145]
	v_mul_f32_e32 v85, 0x45800000, v84
	v_cndmask_b32_e32 v84, v84, v85, vcc
	v_pk_mul_f32 v[80:81], v[80:81], v[84:85] op_sel_hi:[1,0]
	v_pk_mul_f32 v[78:79], v[78:79], v[84:85] op_sel_hi:[1,0]
	v_pk_mul_f32 v[76:77], v[76:77], v[84:85] op_sel_hi:[1,0]
	v_pk_mul_f32 v[74:75], v[74:75], v[84:85] op_sel_hi:[1,0]
	v_pk_mul_f32 v[72:73], v[72:73], v[84:85] op_sel_hi:[1,0]
	v_pk_mul_f32 v[70:71], v[70:71], v[84:85] op_sel_hi:[1,0]
	v_pk_mul_f32 v[86:87], v[68:69], v[84:85] op_sel_hi:[1,0]
	v_pk_mul_f32 v[84:85], v[66:67], v[84:85] op_sel_hi:[1,0]
	v_cvt_pk_bf16_f32 v66, v78, v79
	v_cvt_pk_bf16_f32 v67, v80, v81
	v_cvt_pk_bf16_f32 v68, v74, v75
	v_cvt_pk_bf16_f32 v69, v76, v77
	global_store_dwordx4 v[82:83], v[66:69], off sc1
	s_nop 1
	v_cvt_pk_bf16_f32 v66, v70, v71
	v_cvt_pk_bf16_f32 v67, v72, v73
	v_cvt_pk_bf16_f32 v68, v84, v85
	v_cvt_pk_bf16_f32 v69, v86, v87
	global_store_dwordx4 v[82:83], v[66:69], off offset:256 sc1
	s_nop 0
	s_waitcnt vmcnt(11)
	v_ffbh_u32_e32 v68, v191
	v_min_u32_e32 v68, 32, v68
	v_lshlrev_b64 v[66:67], v68, v[190:191]
	v_min_u32_e32 v66, 1, v66
	v_or_b32_e32 v66, v67, v66
	v_cvt_f32_u32_e32 v66, v66
	v_sub_u32_e32 v68, 32, v68
	v_add_u32_e32 v67, 0x80, v142
	v_ldexp_f32 v66, v66, v68
	v_fmamk_f32 v66, v66, 0x2e000000, v211
	v_mul_f32_e32 v68, 0x4b800000, v66
	v_cmp_gt_f32_e32 vcc, s20, v66
	s_nop 1
	v_cndmask_b32_e32 v66, v66, v68, vcc
	v_rsq_f32_e32 v68, v66
	v_mad_i64_i32 v[66:67], s[0:1], s8, v67, 0
	v_lshl_add_u64 v[66:67], v[66:67], 1, v[144:145]
	v_mul_f32_e32 v69, 0x45800000, v68
	v_cndmask_b32_e32 v68, v68, v69, vcc
	v_pk_mul_f32 v[64:65], v[64:65], v[68:69] op_sel_hi:[1,0]
	v_pk_mul_f32 v[62:63], v[62:63], v[68:69] op_sel_hi:[1,0]
	v_pk_mul_f32 v[60:61], v[60:61], v[68:69] op_sel_hi:[1,0]
	v_pk_mul_f32 v[58:59], v[58:59], v[68:69] op_sel_hi:[1,0]
	v_pk_mul_f32 v[56:57], v[56:57], v[68:69] op_sel_hi:[1,0]
	v_pk_mul_f32 v[54:55], v[54:55], v[68:69] op_sel_hi:[1,0]
	v_pk_mul_f32 v[70:71], v[52:53], v[68:69] op_sel_hi:[1,0]
	v_pk_mul_f32 v[68:69], v[50:51], v[68:69] op_sel_hi:[1,0]
	v_cvt_pk_bf16_f32 v50, v62, v63
	v_cvt_pk_bf16_f32 v51, v64, v65
	v_cvt_pk_bf16_f32 v52, v58, v59
	v_cvt_pk_bf16_f32 v53, v60, v61
	global_store_dwordx4 v[66:67], v[50:53], off sc1
	s_nop 1
	v_cvt_pk_bf16_f32 v50, v54, v55
	v_cvt_pk_bf16_f32 v51, v56, v57
	v_cvt_pk_bf16_f32 v52, v68, v69
	v_cvt_pk_bf16_f32 v53, v70, v71
	global_store_dwordx4 v[66:67], v[50:53], off offset:256 sc1
	s_nop 0
	s_waitcnt vmcnt(12)
	v_ffbh_u32_e32 v52, v193
	v_min_u32_e32 v52, 32, v52
	v_lshlrev_b64 v[50:51], v52, v[192:193]
	v_min_u32_e32 v50, 1, v50
	v_or_b32_e32 v50, v51, v50
	v_cvt_f32_u32_e32 v50, v50
	v_sub_u32_e32 v52, 32, v52
	v_add_u32_e32 v51, 0x90, v142
	v_ldexp_f32 v50, v50, v52
	v_fmamk_f32 v50, v50, 0x2e000000, v211
	v_mul_f32_e32 v52, 0x4b800000, v50
	v_cmp_gt_f32_e32 vcc, s20, v50
	s_nop 1
	v_cndmask_b32_e32 v50, v50, v52, vcc
	v_rsq_f32_e32 v52, v50
	v_mad_i64_i32 v[50:51], s[0:1], s8, v51, 0
	v_lshl_add_u64 v[50:51], v[50:51], 1, v[144:145]
	v_mul_f32_e32 v53, 0x45800000, v52
	v_cndmask_b32_e32 v52, v52, v53, vcc
	v_pk_mul_f32 v[48:49], v[48:49], v[52:53] op_sel_hi:[1,0]
	v_pk_mul_f32 v[46:47], v[46:47], v[52:53] op_sel_hi:[1,0]
	v_pk_mul_f32 v[44:45], v[44:45], v[52:53] op_sel_hi:[1,0]
	v_pk_mul_f32 v[42:43], v[42:43], v[52:53] op_sel_hi:[1,0]
	v_pk_mul_f32 v[40:41], v[40:41], v[52:53] op_sel_hi:[1,0]
	v_pk_mul_f32 v[38:39], v[38:39], v[52:53] op_sel_hi:[1,0]
	v_pk_mul_f32 v[54:55], v[36:37], v[52:53] op_sel_hi:[1,0]
	v_pk_mul_f32 v[52:53], v[34:35], v[52:53] op_sel_hi:[1,0]
	v_cvt_pk_bf16_f32 v34, v46, v47
	v_cvt_pk_bf16_f32 v35, v48, v49
	v_cvt_pk_bf16_f32 v36, v42, v43
	v_cvt_pk_bf16_f32 v37, v44, v45
	global_store_dwordx4 v[50:51], v[34:37], off sc1
	s_nop 1
	v_cvt_pk_bf16_f32 v34, v38, v39
	v_cvt_pk_bf16_f32 v35, v40, v41
	v_cvt_pk_bf16_f32 v36, v52, v53
	v_cvt_pk_bf16_f32 v37, v54, v55
	global_store_dwordx4 v[50:51], v[34:37], off offset:256 sc1
	s_nop 0
	s_waitcnt vmcnt(13)
	v_ffbh_u32_e32 v36, v195
	v_min_u32_e32 v36, 32, v36
	v_lshlrev_b64 v[34:35], v36, v[194:195]
	v_min_u32_e32 v34, 1, v34
	v_or_b32_e32 v34, v35, v34
	v_cvt_f32_u32_e32 v34, v34
	v_sub_u32_e32 v36, 32, v36
	v_add_u32_e32 v35, 0xa0, v142
	v_ldexp_f32 v34, v34, v36
	v_fmamk_f32 v34, v34, 0x2e000000, v211
	v_mul_f32_e32 v36, 0x4b800000, v34
	v_cmp_gt_f32_e32 vcc, s20, v34
	s_nop 1
	v_cndmask_b32_e32 v34, v34, v36, vcc
	v_rsq_f32_e32 v36, v34
	v_mad_i64_i32 v[34:35], s[0:1], s8, v35, 0
	v_lshl_add_u64 v[34:35], v[34:35], 1, v[144:145]
	v_mul_f32_e32 v37, 0x45800000, v36
	v_cndmask_b32_e32 v36, v36, v37, vcc
	v_pk_mul_f32 v[32:33], v[32:33], v[36:37] op_sel_hi:[1,0]
	v_pk_mul_f32 v[30:31], v[30:31], v[36:37] op_sel_hi:[1,0]
	v_pk_mul_f32 v[28:29], v[28:29], v[36:37] op_sel_hi:[1,0]
	v_pk_mul_f32 v[26:27], v[26:27], v[36:37] op_sel_hi:[1,0]
	v_pk_mul_f32 v[24:25], v[24:25], v[36:37] op_sel_hi:[1,0]
	v_pk_mul_f32 v[22:23], v[22:23], v[36:37] op_sel_hi:[1,0]
	v_pk_mul_f32 v[38:39], v[20:21], v[36:37] op_sel_hi:[1,0]
	v_pk_mul_f32 v[36:37], v[18:19], v[36:37] op_sel_hi:[1,0]
	v_cvt_pk_bf16_f32 v18, v30, v31
	v_cvt_pk_bf16_f32 v19, v32, v33
	v_cvt_pk_bf16_f32 v20, v26, v27
	v_cvt_pk_bf16_f32 v21, v28, v29
	global_store_dwordx4 v[34:35], v[18:21], off sc1
	s_andn2_b64 vcc, exec, s[36:37]
	s_nop 0
	v_cvt_pk_bf16_f32 v18, v22, v23
	v_cvt_pk_bf16_f32 v19, v24, v25
	v_cvt_pk_bf16_f32 v20, v36, v37
	v_cvt_pk_bf16_f32 v21, v38, v39
	global_store_dwordx4 v[34:35], v[18:21], off offset:256 sc1
	s_nop 0
	s_nop 0
	v_add_u32_e32 v20, 0xb0, v142
	s_waitcnt vmcnt(14)
	v_ffbh_u32_e32 v21, v197
	v_min_u32_e32 v21, 32, v21
	v_lshlrev_b64 v[18:19], v21, v[196:197]
	v_min_u32_e32 v18, 1, v18
	v_or_b32_e32 v18, v19, v18
	v_cvt_f32_u32_e32 v18, v18
	v_sub_u32_e32 v19, 32, v21
	v_ldexp_f32 v18, v18, v19
	v_fmamk_f32 v18, v18, 0x2e000000, v211
	v_mul_f32_e32 v19, 0x4b800000, v18
	v_cmp_gt_f32_e64 s[0:1], s20, v18
	s_nop 1
	v_cndmask_b32_e64 v18, v18, v19, s[0:1]
	v_rsq_f32_e32 v21, v18
	v_mad_i64_i32 v[18:19], s[8:9], s8, v20, 0
	v_lshl_add_u64 v[18:19], v[18:19], 1, v[144:145]
	v_mul_f32_e32 v20, 0x45800000, v21
	v_cndmask_b32_e64 v20, v21, v20, s[0:1]
	v_pk_mul_f32 v[16:17], v[16:17], v[20:21] op_sel_hi:[1,0]
	v_pk_mul_f32 v[14:15], v[14:15], v[20:21] op_sel_hi:[1,0]
	v_pk_mul_f32 v[12:13], v[12:13], v[20:21] op_sel_hi:[1,0]
	v_pk_mul_f32 v[10:11], v[10:11], v[20:21] op_sel_hi:[1,0]
	v_pk_mul_f32 v[8:9], v[8:9], v[20:21] op_sel_hi:[1,0]
	v_pk_mul_f32 v[6:7], v[6:7], v[20:21] op_sel_hi:[1,0]
	v_pk_mul_f32 v[22:23], v[4:5], v[20:21] op_sel_hi:[1,0]
	v_pk_mul_f32 v[20:21], v[2:3], v[20:21] op_sel_hi:[1,0]
	v_cvt_pk_bf16_f32 v2, v14, v15
	v_cvt_pk_bf16_f32 v3, v16, v17
	v_cvt_pk_bf16_f32 v4, v10, v11
	v_cvt_pk_bf16_f32 v5, v12, v13
	s_mov_b64 s[0:1], -1
	global_store_dwordx4 v[18:19], v[2:5], off sc1
	s_nop 1
	v_cvt_pk_bf16_f32 v2, v6, v7
	v_cvt_pk_bf16_f32 v3, v8, v9
	v_cvt_pk_bf16_f32 v4, v20, v21
	v_cvt_pk_bf16_f32 v5, v22, v23
	global_store_dwordx4 v[18:19], v[2:5], off offset:256 sc1
	s_cbranch_vccnz .LBB0_249
	s_andn2_b64 vcc, exec, s[38:39]
	s_cbranch_vccnz .LBB0_248
	s_barrier
	s_branch .LBB0_248

.LBB0_335:
	global_atomic_add v4, v[170:171], v212, off sc0
	v_cvt_f32_u32_e32 v2, v3
	v_sub_u32_e32 v5, 0, v3
	v_rcp_iflag_f32_e32 v2, v2
	s_nop 0
	v_mul_f32_e32 v2, 0x4f7ffffe, v2
	v_cvt_u32_f32_e32 v2, v2
	v_mul_lo_u32 v5, v5, v2
	v_mul_hi_u32 v5, v2, v5
	v_add_u32_e32 v2, v2, v5
	s_waitcnt vmcnt(0)
	v_mul_hi_u32 v2, v4, v2
	v_mul_lo_u32 v5, v2, v3
	v_sub_u32_e32 v5, v4, v5
	v_add_u32_e32 v6, 1, v2
	v_sub_u32_e32 v7, v5, v3
	v_cmp_ge_u32_e32 vcc, v5, v3
	v_add_u32_e32 v4, 1, v4
	s_nop 0
	v_cndmask_b32_e32 v2, v2, v6, vcc
	v_cndmask_b32_e32 v5, v5, v7, vcc
	v_add_u32_e32 v6, 1, v2
	v_cmp_ge_u32_e32 vcc, v5, v3
	s_nop 1
	v_cndmask_b32_e32 v2, v2, v6, vcc
	v_mul_lo_u32 v5, v3, v2
	v_add_u32_e32 v3, v5, v3
	v_cmp_ne_u32_e32 vcc, v4, v3
	s_and_saveexec_b64 s[4:5], vcc
	s_xor_b64 s[6:7], exec, s[4:5]
	s_cbranch_execz .LBB0_349
	s_waitcnt lgkmcnt(0)
	v_mov_b32_e32 v1, 0x3300
	global_load_dword v1, v1, s[22:23] sc1
	s_waitcnt vmcnt(0)
	v_cmp_eq_u32_e32 vcc, v1, v2
	s_and_saveexec_b64 s[8:9], vcc
	s_cbranch_execz .LBB0_348
	s_mov_b32 s3, 1
	s_mov_b64 s[24:25], 0
	s_branch .LBB0_339

.LBB0_341:
	v_mov_b32_e32 v1, 0x3300
	global_load_dword v1, v1, s[22:23] sc1
	s_add_i32 s3, s3, 1
	s_mov_b64 s[40:41], -1
	s_waitcnt vmcnt(0)
	v_cmp_ne_u32_e32 vcc, v1, v2
	s_orn2_b64 s[38:39], vcc, exec
	s_branch .LBB0_338

.LBB0_472:
	global_atomic_add v4, v[170:171], v212, off sc0
	v_cvt_f32_u32_e32 v1, v3
	v_sub_u32_e32 v5, 0, v3
	v_rcp_iflag_f32_e32 v1, v1
	s_nop 0
	v_mul_f32_e32 v1, 0x4f7ffffe, v1
	v_cvt_u32_f32_e32 v1, v1
	v_mul_lo_u32 v5, v5, v1
	v_mul_hi_u32 v5, v1, v5
	v_add_u32_e32 v1, v1, v5
	s_waitcnt vmcnt(0)
	v_mul_hi_u32 v1, v4, v1
	v_mul_lo_u32 v5, v1, v3
	v_sub_u32_e32 v5, v4, v5
	v_add_u32_e32 v6, 1, v1
	v_cmp_ge_u32_e32 vcc, v5, v3
	v_add_u32_e32 v4, 1, v4
	s_nop 0
	v_cndmask_b32_e32 v1, v1, v6, vcc
	v_sub_u32_e32 v6, v5, v3
	v_cndmask_b32_e32 v5, v5, v6, vcc
	v_add_u32_e32 v6, 1, v1
	v_cmp_ge_u32_e32 vcc, v5, v3
	s_nop 1
	v_cndmask_b32_e32 v1, v1, v6, vcc
	v_mul_lo_u32 v5, v3, v1
	v_add_u32_e32 v3, v5, v3
	v_cmp_ne_u32_e32 vcc, v4, v3
	s_and_saveexec_b64 s[4:5], vcc
	s_xor_b64 s[6:7], exec, s[4:5]
	s_cbranch_execz .LBB0_486
	s_waitcnt lgkmcnt(0)
	v_mov_b32_e32 v2, 0x3300
	global_load_dword v2, v2, s[22:23] sc1
	s_waitcnt vmcnt(0)
	v_cmp_eq_u32_e32 vcc, v2, v1
	s_and_saveexec_b64 s[8:9], vcc
	s_cbranch_execz .LBB0_485
	s_mov_b32 s3, 1
	s_mov_b64 s[36:37], 0
	s_branch .LBB0_476

.LBB0_478:
	v_mov_b32_e32 v2, 0x3300
	global_load_dword v2, v2, s[22:23] sc1
	s_add_i32 s3, s3, 1
	s_mov_b64 s[44:45], -1
	s_waitcnt vmcnt(0)
	v_cmp_ne_u32_e32 vcc, v2, v1
	s_orn2_b64 s[40:41], vcc, exec
	s_branch .LBB0_475

.LBB0_514:
	v_ashrrev_i32_e32 v6, 4, v147
	v_ashrrev_i32_e32 v7, 31, v6
	v_lshlrev_b64 v[2:3], 13, v[6:7]
	v_lshl_add_u64 v[2:3], v[144:145], 0, v[2:3]
	s_mov_b32 s4, 0x40000
	s_mov_b32 s5, 0
	v_mad_u32_u24 v6, v6, s11, v146
	global_load_dwordx4 v[48:51], v[2:3], off
	v_lshl_add_u64 v[2:3], v[2:3], 0, s[4:5]
	global_load_dwordx4 v[52:55], v[2:3], off
	v_lshl_add_u64 v[2:3], v[2:3], 0, s[4:5]
	global_load_dwordx4 v[56:59], v[2:3], off
	v_lshl_add_u64 v[2:3], v[2:3], 0, s[4:5]
	global_load_dwordx4 v[60:63], v[2:3], off
	v_lshl_add_u64 v[2:3], v[2:3], 0, s[4:5]
	global_load_dwordx4 v[64:67], v[2:3], off
	v_lshl_add_u64 v[2:3], v[2:3], 0, s[4:5]
	global_load_dwordx4 v[68:71], v[2:3], off
	v_lshl_add_u64 v[2:3], v[2:3], 0, s[4:5]
	global_load_dwordx4 v[72:75], v[2:3], off
	v_lshl_add_u64 v[2:3], v[2:3], 0, s[4:5]
	global_load_dwordx4 v[76:79], v[2:3], off
	s_waitcnt vmcnt(7)
	ds_write_b128 v6, v[48:51]
	s_waitcnt vmcnt(6)
	ds_write_b128 v6, v[52:55] offset:8704
	s_waitcnt vmcnt(5)
	ds_write_b128 v6, v[56:59] offset:17408
	s_waitcnt vmcnt(4)
	ds_write_b128 v6, v[60:63] offset:26112
	s_waitcnt vmcnt(3)
	ds_write_b128 v6, v[64:67] offset:34816
	s_waitcnt vmcnt(2)
	ds_write_b128 v6, v[68:71] offset:43520
	s_waitcnt vmcnt(1)
	ds_write_b128 v6, v[72:75] offset:52224
	s_waitcnt vmcnt(0)
	ds_write_b128 v6, v[76:79] offset:60928
	s_movk_i32 s3, 0x1000
	s_lshl_b32 s9, s1, 1
	s_add_u32 s92, s96, s9
	s_addc_u32 s93, s97, 0
	s_add_u32 s40, s29, s9
	s_addc_u32 s41, s80, 0
	s_ashr_i32 s4, s0, 6
	v_and_b32_e32 v205, 31, v147
	s_lshl_b32 s26, s4, 5
	v_or_b32_e32 v1, s26, v205
	v_bfe_u32 v149, v147, 5, 1
	v_mul_lo_u32 v1, v1, s11
	s_lshl_b32 s3, s6, 8
	v_add_u32_e32 v151, 0, v1
	v_lshlrev_b32_e32 v180, 4, v149
	v_add_u32_e32 v1, v151, v180
	v_ashrrev_i32_e32 v182, 4, v147
	s_or_b32 s5, s3, 0xc0
	s_waitcnt lgkmcnt(0)
	s_barrier
	ds_read_b128 v[96:99], v1
	ds_read_b128 v[100:103], v1 offset:32
	ds_read_b128 v[104:107], v1 offset:64
	ds_read_b128 v[108:111], v1 offset:96
	ds_read_b128 v[112:115], v1 offset:128
	ds_read_b128 v[116:119], v1 offset:160
	ds_read_b128 v[120:123], v1 offset:192
	ds_read_b128 v[124:127], v1 offset:224
	v_add_u32_e32 v1, s5, v182
	v_add_u32_e32 v10, 32, v1
	v_mad_i64_i32 v[2:3], s[0:1], v1, s91, 0
	v_mad_i64_i32 v[10:11], s[0:1], v10, s91, 0
	v_or_b32_e32 v2, v2, v148
	v_or_b32_e32 v10, v10, v148
	v_lshlrev_b64 v[2:3], 1, v[2:3]
	v_lshlrev_b64 v[10:11], 1, v[10:11]
	v_lshl_add_u64 v[4:5], s[92:93], 0, v[2:3]
	v_lshl_add_u64 v[6:7], s[40:41], 0, v[2:3]
	v_lshl_add_u64 v[12:13], s[92:93], 0, v[10:11]
	v_lshl_add_u64 v[14:15], s[40:41], 0, v[10:11]
	s_waitcnt lgkmcnt(0)
	s_barrier
	global_load_dwordx4 v[2:5], v[4:5], off
	s_nop 0
	global_load_dwordx4 v[6:9], v[6:7], off
	s_nop 0
	global_load_dwordx4 v[10:13], v[12:13], off
	s_nop 0
	global_load_dwordx4 v[14:17], v[14:15], off
	s_movk_i32 s0, 0x140
	v_subrev_u32_e32 v18, 64, v1
	v_mul_lo_u32 v184, v182, s0
	v_subrev_u32_e32 v1, 32, v1
	v_mad_i64_i32 v[18:19], s[0:1], v18, s91, 0
	v_mad_i64_i32 v[20:21], s[0:1], v1, s91, 0
	v_or_b32_e32 v18, v18, v148
	v_mul_lo_u32 v183, v182, s11
	v_or_b32_e32 v20, v20, v148
	v_lshlrev_b64 v[18:19], 1, v[18:19]
	v_add_u32_e32 v26, v146, v183
	v_lshlrev_b64 v[20:21], 1, v[20:21]
	v_lshl_add_u64 v[22:23], s[92:93], 0, v[18:19]
	v_add_u32_e32 v27, v146, v184
	v_lshl_add_u64 v[18:19], s[40:41], 0, v[18:19]
	v_lshl_add_u64 v[24:25], s[92:93], 0, v[20:21]
	v_lshl_add_u64 v[20:21], s[40:41], 0, v[20:21]
	s_add_i32 s26, s26, s3
	v_lshrrev_b32_e32 v1, 2, v147
	v_lshlrev_b32_e32 v186, 2, v149
	v_and_b32_e32 v206, 63, v147
	v_and_or_b32 v1, v1, 3, v186
	s_or_b32 s3, s26, 31
	v_or_b32_e32 v185, s26, v205
	v_mul_u32_u24_e32 v187, 0x140, v1
	v_cmp_gt_u32_e64 s[36:37], 32, v206
	v_or_b32_e32 v190, 24, v186
	v_or_b32_e32 v191, 25, v186
	v_or_b32_e32 v192, 26, v186
	v_or_b32_e32 v193, 27, v186
	v_or_b32_e32 v194, 16, v186
	v_or_b32_e32 v195, 17, v186
	v_or_b32_e32 v196, 18, v186
	v_or_b32_e32 v197, 19, v186
	v_or_b32_e32 v198, 8, v186
	v_or_b32_e32 v199, 9, v186
	v_or_b32_e32 v200, 10, v186
	v_or_b32_e32 v201, 11, v186
	v_or_b32_e32 v202, 1, v186
	v_or_b32_e32 v203, 2, v186
	s_cmp_le_i32 s5, s3
	v_or_b32_e32 v204, 3, v186
	s_mov_b32 s86, 0xd9c7dd
	s_waitcnt vmcnt(3)
	ds_write_b128 v26, v[2:5]
	s_waitcnt vmcnt(2)
	ds_write_b128 v27, v[6:9] offset:34816
	s_waitcnt vmcnt(1)
	ds_write_b128 v26, v[10:13] offset:8704
	s_waitcnt vmcnt(0)
	ds_write_b128 v27, v[14:17] offset:45056
	s_waitcnt lgkmcnt(0)
	s_barrier
	global_load_dwordx4 v[128:131], v[22:23], off
	global_load_dwordx4 v[132:135], v[18:19], off
	global_load_dwordx4 v[136:139], v[24:25], off
	global_load_dwordx4 v[140:143], v[20:21], off
	v_lshlrev_b32_e32 v2, 1, v147
	v_lshlrev_b32_e32 v3, 3, v147
	v_and_b32_e32 v188, 32, v2
	v_and_b32_e32 v189, 24, v3
	s_cbranch_scc0 .LBB0_524
	v_add_u32_e32 v1, 0, v180
	s_or_b32 s21, s5, 32
	v_add3_u32 v207, 0, v187, v188
	s_cmp_gt_i32 s21, s3
	v_mad_u32_u24 v152, v205, s11, v1
	s_cbranch_scc1 .LBB0_525
	ds_read_b128 v[2:5], v152 offset:8704
	ds_read_b128 v[18:21], v152 offset:8736
	ds_read_b128 v[222:225], v152 offset:8768
	ds_read_b128 v[226:229], v152 offset:8800
	ds_read_b128 v[230:233], v152 offset:8832
	ds_read_b128 v[234:237], v152 offset:8864
	ds_read_b128 v[238:241], v152 offset:8896
	ds_read_b128 v[242:245], v152 offset:8928
	s_or_b32 s12, s5, 63
	s_mov_b64 s[0:1], -1
	s_cmp_lt_i32 s12, s26
	s_waitcnt lgkmcnt(7)
	v_mfma_f32_32x32x16_bf16 v[2:17], v[2:5], v[96:99], 0
	s_waitcnt lgkmcnt(6)
	v_mfma_f32_32x32x16_bf16 v[2:17], v[18:21], v[100:103], v[2:17]
	s_waitcnt lgkmcnt(5)
	v_mfma_f32_32x32x16_bf16 v[2:17], v[222:225], v[104:107], v[2:17]
	s_waitcnt lgkmcnt(4)
	v_mfma_f32_32x32x16_bf16 v[2:17], v[226:229], v[108:111], v[2:17]
	s_waitcnt lgkmcnt(3)
	v_mfma_f32_32x32x16_bf16 v[2:17], v[230:233], v[112:115], v[2:17]
	s_waitcnt lgkmcnt(2)
	v_mfma_f32_32x32x16_bf16 v[2:17], v[234:237], v[116:119], v[2:17]
	s_waitcnt lgkmcnt(1)
	v_mfma_f32_32x32x16_bf16 v[2:17], v[238:241], v[120:123], v[2:17]
	s_waitcnt lgkmcnt(0)
	v_mfma_f32_32x32x16_bf16 v[2:17], v[242:245], v[124:127], v[2:17]
	s_nop 11
	v_mul_f32_e32 v46, 0x3e0293ee, v3
	v_mul_f32_e32 v1, 0x3e0293ee, v5
	s_cbranch_scc1 .LBB0_519
	v_and_b32_e32 v18, 64, v217
	v_xor_b32_e32 v3, 32, v217
	v_add_u32_e32 v18, 64, v18
	v_cmp_lt_i32_e32 vcc, v3, v18
	v_mul_f32_e32 v18, 0x3e0293ee, v14
	v_exp_f32_e64 v19, -|v18|
	v_subrev_u32_e32 v5, s21, v185
	v_cndmask_b32_e32 v3, v217, v3, vcc
	v_cmp_lt_f32_e32 vcc, 0, v18
	v_add_f32_e32 v20, 1.0, v19
	v_rcp_f32_e32 v20, v20
	v_lshlrev_b32_e32 v3, 2, v3
	s_mov_b64 s[0:1], 0
	v_mul_f32_e32 v19, v19, v20
	v_cndmask_b32_e32 v18, v19, v20, vcc
	v_cndmask_b32_e32 v19, v20, v19, vcc
	v_cmp_lt_i32_e32 vcc, v190, v5
	s_nop 1
	v_cndmask_b32_e32 v20, 1.0, v19, vcc
	v_mul_f32_e32 v19, 0x3e0293ee, v15
	v_exp_f32_e64 v21, -|v19|
	v_cndmask_b32_e32 v18, 0, v18, vcc
	v_cmp_lt_f32_e32 vcc, 0, v19
	v_mov_b32_e32 v19, s27
	v_add_f32_e32 v22, 1.0, v21
	v_rcp_f32_e32 v22, v22
	s_nop 0
	v_mul_f32_e32 v21, v21, v22
	v_cndmask_b32_e32 v23, v21, v22, vcc
	v_cndmask_b32_e32 v21, v22, v21, vcc
	v_cmp_lt_i32_e32 vcc, v191, v5
	s_nop 1
	v_cndmask_b32_e32 v22, 1.0, v21, vcc
	v_mul_f32_e32 v21, v20, v22
	v_mul_f32_e32 v20, 0x3e0293ee, v16
	v_cndmask_b32_e32 v19, v19, v23, vcc
	v_exp_f32_e64 v23, -|v20|
	v_cmp_lt_f32_e32 vcc, 0, v20
	v_mov_b32_e32 v20, s27
	v_add_f32_e32 v24, 1.0, v23
	v_rcp_f32_e32 v24, v24
	s_nop 0
	v_mul_f32_e32 v23, v23, v24
	v_cndmask_b32_e32 v25, v23, v24, vcc
	v_cndmask_b32_e32 v23, v24, v23, vcc
	v_cmp_lt_i32_e32 vcc, v192, v5
	s_nop 1
	v_cndmask_b32_e32 v23, 1.0, v23, vcc
	v_mul_f32_e32 v24, v23, v21
	v_mul_f32_e32 v21, 0x3e0293ee, v17
	v_cndmask_b32_e32 v20, v20, v25, vcc
	v_exp_f32_e64 v25, -|v21|
	v_cmp_lt_f32_e32 vcc, 0, v21
	v_mov_b32_e32 v21, s27
	v_add_f32_e32 v26, 1.0, v25
	v_rcp_f32_e32 v26, v26
	s_nop 0
	v_mul_f32_e32 v25, v25, v26
	v_cndmask_b32_e32 v27, v25, v26, vcc
	v_cndmask_b32_e32 v25, v26, v25, vcc
	v_cmp_lt_i32_e32 vcc, v193, v5
	s_nop 1
	v_cndmask_b32_e32 v26, 1.0, v25, vcc
	v_cndmask_b32_e32 v21, v21, v27, vcc
	v_mul_f32_e32 v27, v26, v24
	ds_bpermute_b32 v28, v3, v27
	s_waitcnt lgkmcnt(0)
	v_cndmask_b32_e64 v25, 1.0, v28, s[36:37]
	v_mul_f32_e32 v24, v26, v25
	v_mul_f32_e32 v26, 0x3e0293ee, v10
	v_mul_f32_e32 v34, v27, v28
	v_exp_f32_e64 v27, -|v26|
	v_cmp_lt_f32_e32 vcc, 0, v26
	v_mov_b32_e32 v26, s27
	v_mul_f32_e32 v23, v23, v24
	v_add_f32_e32 v28, 1.0, v27
	v_rcp_f32_e32 v28, v28
	v_mul_f32_e32 v22, v22, v23
	v_pk_mul_f32 v[20:21], v[20:21], v[24:25]
	v_pk_mul_f32 v[18:19], v[18:19], v[22:23]
	v_mul_f32_e32 v27, v27, v28
	v_cndmask_b32_e32 v29, v27, v28, vcc
	v_cndmask_b32_e32 v27, v28, v27, vcc
	v_cmp_lt_i32_e32 vcc, v194, v5
	s_nop 1
	v_cndmask_b32_e32 v28, 1.0, v27, vcc
	v_mul_f32_e32 v27, 0x3e0293ee, v11
	v_cndmask_b32_e32 v26, v26, v29, vcc
	v_exp_f32_e64 v29, -|v27|
	v_cmp_lt_f32_e32 vcc, 0, v27
	v_mov_b32_e32 v27, s27
	v_add_f32_e32 v30, 1.0, v29
	v_rcp_f32_e32 v30, v30
	s_nop 0
	v_mul_f32_e32 v29, v29, v30
	v_cndmask_b32_e32 v31, v29, v30, vcc
	v_cndmask_b32_e32 v29, v30, v29, vcc
	v_cmp_lt_i32_e32 vcc, v195, v5
	s_nop 1
	v_cndmask_b32_e32 v30, 1.0, v29, vcc
	v_mul_f32_e32 v29, v28, v30
	v_mul_f32_e32 v28, 0x3e0293ee, v12
	v_cndmask_b32_e32 v27, v27, v31, vcc
	v_exp_f32_e64 v31, -|v28|
	v_cmp_lt_f32_e32 vcc, 0, v28
	v_mov_b32_e32 v28, s27
	v_add_f32_e32 v32, 1.0, v31
	v_rcp_f32_e32 v32, v32
	s_nop 0
	v_mul_f32_e32 v31, v31, v32
	v_cndmask_b32_e32 v33, v31, v32, vcc
	v_cndmask_b32_e32 v31, v32, v31, vcc
	v_cmp_lt_i32_e32 vcc, v196, v5
	s_nop 1
	v_cndmask_b32_e32 v31, 1.0, v31, vcc
	v_mul_f32_e32 v32, v31, v29
	v_mul_f32_e32 v29, 0x3e0293ee, v13
	v_cndmask_b32_e32 v28, v28, v33, vcc
	v_exp_f32_e64 v33, -|v29|
	v_cmp_lt_f32_e32 vcc, 0, v29
	v_mov_b32_e32 v29, s27
	v_add_f32_e32 v35, 1.0, v33
	v_rcp_f32_e32 v35, v35
	s_nop 0
	v_mul_f32_e32 v33, v33, v35
	v_cndmask_b32_e32 v36, v33, v35, vcc
	v_cndmask_b32_e32 v33, v35, v33, vcc
	v_cmp_lt_i32_e32 vcc, v197, v5
	s_nop 1
	v_cndmask_b32_e32 v35, 1.0, v33, vcc
	v_cndmask_b32_e32 v29, v29, v36, vcc
	v_mul_f32_e32 v36, v35, v32
	ds_bpermute_b32 v37, v3, v36
	s_waitcnt lgkmcnt(0)
	v_cndmask_b32_e64 v32, 1.0, v37, s[36:37]
	v_mul_f32_e32 v33, v34, v32
	v_mul_f32_e32 v32, v35, v33
	v_mul_f32_e32 v35, v36, v37
	v_mul_f32_e32 v42, v34, v35
	v_mul_f32_e32 v34, 0x3e0293ee, v6
	v_exp_f32_e64 v35, -|v34|
	v_cmp_lt_f32_e32 vcc, 0, v34
	v_mov_b32_e32 v34, s27
	v_mul_f32_e32 v31, v31, v32
	v_add_f32_e32 v36, 1.0, v35
	v_rcp_f32_e32 v36, v36
	v_mul_f32_e32 v30, v30, v31
	v_pk_mul_f32 v[28:29], v[28:29], v[32:33]
	v_pk_mul_f32 v[26:27], v[26:27], v[30:31]
	v_mul_f32_e32 v35, v35, v36
	v_cndmask_b32_e32 v37, v35, v36, vcc
	v_cndmask_b32_e32 v35, v36, v35, vcc
	v_cmp_lt_i32_e32 vcc, v198, v5
	s_nop 1
	v_cndmask_b32_e32 v36, 1.0, v35, vcc
	v_mul_f32_e32 v35, 0x3e0293ee, v7
	v_cndmask_b32_e32 v34, v34, v37, vcc
	v_exp_f32_e64 v37, -|v35|
	v_cmp_lt_f32_e32 vcc, 0, v35
	v_mov_b32_e32 v35, s27
	v_add_f32_e32 v38, 1.0, v37
	v_rcp_f32_e32 v38, v38
	s_nop 0
	v_mul_f32_e32 v37, v37, v38
	v_cndmask_b32_e32 v39, v37, v38, vcc
	v_cndmask_b32_e32 v37, v38, v37, vcc
	v_cmp_lt_i32_e32 vcc, v199, v5
	s_nop 1
	v_cndmask_b32_e32 v38, 1.0, v37, vcc
	v_mul_f32_e32 v37, v36, v38
	v_mul_f32_e32 v36, 0x3e0293ee, v8
	v_cndmask_b32_e32 v35, v35, v39, vcc
	v_exp_f32_e64 v39, -|v36|
	v_cmp_lt_f32_e32 vcc, 0, v36
	v_mov_b32_e32 v36, s27
	v_add_f32_e32 v40, 1.0, v39
	v_rcp_f32_e32 v40, v40
	s_nop 0
	v_mul_f32_e32 v39, v39, v40
	v_cndmask_b32_e32 v41, v39, v40, vcc
	v_cndmask_b32_e32 v39, v40, v39, vcc
	v_cmp_lt_i32_e32 vcc, v200, v5
	s_nop 1
	v_cndmask_b32_e32 v39, 1.0, v39, vcc
	v_mul_f32_e32 v40, v39, v37
	v_mul_f32_e32 v37, 0x3e0293ee, v9
	v_cndmask_b32_e32 v36, v36, v41, vcc
	v_exp_f32_e64 v41, -|v37|
	v_cmp_lt_f32_e32 vcc, 0, v37
	v_mov_b32_e32 v37, s27
	v_add_f32_e32 v43, 1.0, v41
	v_rcp_f32_e32 v43, v43
	s_nop 0
	v_mul_f32_e32 v41, v41, v43
	v_cndmask_b32_e32 v44, v41, v43, vcc
	v_cndmask_b32_e32 v41, v43, v41, vcc
	v_cmp_lt_i32_e32 vcc, v201, v5
	s_nop 1
	v_cndmask_b32_e32 v43, 1.0, v41, vcc
	v_cndmask_b32_e32 v37, v37, v44, vcc
	v_mul_f32_e32 v44, v43, v40
	ds_bpermute_b32 v45, v3, v44
	s_waitcnt lgkmcnt(0)
	v_cndmask_b32_e64 v40, 1.0, v45, s[36:37]
	v_mul_f32_e32 v41, v42, v40
	v_mul_f32_e32 v40, v43, v41
	v_mul_f32_e32 v43, v44, v45
	v_mul_f32_e32 v47, v43, v42
	v_mul_f32_e32 v42, 0x3e0293ee, v2
	v_exp_f32_e64 v43, -|v42|
	v_cmp_lt_f32_e32 vcc, 0, v42
	v_mov_b32_e32 v42, s27
	v_mul_f32_e32 v39, v39, v40
	v_add_f32_e32 v44, 1.0, v43
	v_rcp_f32_e32 v44, v44
	v_mul_f32_e32 v38, v38, v39
	v_pk_mul_f32 v[36:37], v[36:37], v[40:41]
	v_pk_mul_f32 v[34:35], v[34:35], v[38:39]
	v_mul_f32_e32 v43, v43, v44
	v_cndmask_b32_e32 v45, v43, v44, vcc
	v_cndmask_b32_e32 v43, v44, v43, vcc
	v_cmp_lt_i32_e32 vcc, v186, v5
	s_nop 1
	v_cndmask_b32_e32 v44, 1.0, v43, vcc
	v_exp_f32_e64 v43, -|v46|
	v_cndmask_b32_e32 v42, v42, v45, vcc
	v_cmp_lt_f32_e32 vcc, 0, v46
	v_add_f32_e32 v45, 1.0, v43
	v_rcp_f32_e32 v45, v45
	s_nop 0
	v_mul_f32_e32 v43, v43, v45
	v_cndmask_b32_e32 v48, v43, v45, vcc
	v_cndmask_b32_e32 v45, v45, v43, vcc
	v_cmp_lt_i32_e32 vcc, v202, v5
	v_mov_b32_e32 v43, s27
	s_nop 0
	v_cndmask_b32_e32 v50, 1.0, v45, vcc
	v_mul_f32_e32 v45, v44, v50
	v_mul_f32_e32 v44, 0x3e0293ee, v4
	v_cndmask_b32_e32 v43, v43, v48, vcc
	v_exp_f32_e64 v48, -|v44|
	v_cmp_lt_f32_e32 vcc, 0, v44
	v_mov_b32_e32 v44, s27
	v_add_f32_e32 v49, 1.0, v48
	v_rcp_f32_e32 v49, v49
	s_nop 0
	v_mul_f32_e32 v48, v48, v49
	v_cndmask_b32_e32 v51, v48, v49, vcc
	v_cndmask_b32_e32 v48, v49, v48, vcc
	v_cmp_lt_i32_e32 vcc, v203, v5
	s_nop 1
	v_cndmask_b32_e32 v44, v44, v51, vcc
	v_cndmask_b32_e32 v51, 1.0, v48, vcc
	v_mul_f32_e32 v48, v51, v45
	v_exp_f32_e64 v45, -|v1|
	v_cmp_lt_f32_e32 vcc, 0, v1
	v_add_f32_e32 v49, 1.0, v45
	v_rcp_f32_e32 v49, v49
	s_nop 0
	v_mul_f32_e32 v45, v45, v49
	v_cndmask_b32_e32 v52, v45, v49, vcc
	v_cndmask_b32_e32 v49, v49, v45, vcc
	v_cmp_lt_i32_e32 vcc, v204, v5
	v_mov_b32_e32 v5, s27
	s_nop 0
	v_cndmask_b32_e32 v45, v5, v52, vcc
	v_cndmask_b32_e32 v5, 1.0, v49, vcc
	v_mul_f32_e32 v52, v5, v48
	ds_bpermute_b32 v3, v3, v52
	s_waitcnt lgkmcnt(0)
	v_cndmask_b32_e64 v48, 1.0, v3, s[36:37]
	v_mul_f32_e32 v49, v47, v48
	v_mul_f32_e32 v48, v5, v49
	v_mul_f32_e32 v51, v51, v48
	v_mul_f32_e32 v50, v50, v51
	v_mul_f32_e32 v3, v52, v3
	v_pk_mul_f32 v[44:45], v[44:45], v[48:49]
	v_pk_mul_f32 v[42:43], v[42:43], v[50:51]
	v_mul_f32_e32 v153, v3, v47

.LBB0_521:
	v_add_u32_e32 v1, v207, v189
	ds_read_b64_tr_b16 v[222:223], v1 offset:45056
	ds_read_b64_tr_b16 v[224:225], v1 offset:47616
	ds_read_b64_tr_b16 v[226:227], v1 offset:50176
	ds_read_b64_tr_b16 v[228:229], v1 offset:52736
	ds_read_b64_tr_b16 v[230:231], v1 offset:45120
	ds_read_b64_tr_b16 v[232:233], v1 offset:47680
	ds_read_b64_tr_b16 v[234:235], v1 offset:50240
	ds_read_b64_tr_b16 v[236:237], v1 offset:52800
	ds_read_b64_tr_b16 v[238:239], v1 offset:45184
	ds_read_b64_tr_b16 v[240:241], v1 offset:47744
	ds_read_b64_tr_b16 v[242:243], v1 offset:50304
	ds_read_b64_tr_b16 v[244:245], v1 offset:52864
	v_cvt_pk_bf16_f32 v2, v42, v43
	v_cvt_pk_bf16_f32 v3, v44, v45
	v_cvt_pk_bf16_f32 v4, v34, v35
	v_cvt_pk_bf16_f32 v5, v36, v37
	v_cvt_pk_bf16_f32 v6, v26, v27
	v_cvt_pk_bf16_f32 v7, v28, v29
	v_cvt_pk_bf16_f32 v8, v18, v19
	v_cvt_pk_bf16_f32 v9, v20, v21
	s_waitcnt lgkmcnt(10)
	v_mfma_f32_32x32x16_bf16 v[16:31], v[222:225], v[2:5], 0
	ds_read_b64_tr_b16 v[84:85], v1 offset:45248
	ds_read_b64_tr_b16 v[86:87], v1 offset:47808
	s_waitcnt lgkmcnt(10)
	v_mfma_f32_32x32x16_bf16 v[16:31], v[226:229], v[6:9], v[16:31]
	ds_read_b64_tr_b16 v[88:89], v1 offset:50368
	ds_read_b64_tr_b16 v[90:91], v1 offset:52928
	s_waitcnt lgkmcnt(10)
	v_mfma_f32_32x32x16_bf16 v[32:47], v[230:233], v[2:5], 0
	s_waitcnt lgkmcnt(8)
	v_mfma_f32_32x32x16_bf16 v[32:47], v[234:237], v[6:9], v[32:47]
	s_waitcnt lgkmcnt(6)
	v_mfma_f32_32x32x16_bf16 v[48:63], v[238:241], v[2:5], 0
	s_waitcnt lgkmcnt(4)
	v_mfma_f32_32x32x16_bf16 v[48:63], v[242:245], v[6:9], v[48:63]
	s_waitcnt lgkmcnt(2)
	v_mfma_f32_32x32x16_bf16 v[64:79], v[84:87], v[2:5], 0
	s_waitcnt lgkmcnt(0)
	v_mfma_f32_32x32x16_bf16 v[64:79], v[88:91], v[6:9], v[64:79]
	v_cmp_gt_f32_e32 vcc, s86, v153
	s_cmp_eq_u64 vcc, -1
	s_cbranch_scc0 .LBB0_526
	s_branch .LBB0_531

.LBB0_526:
	ds_read_b128 v[2:5], v152
	ds_read_b128 v[6:9], v152 offset:32
	ds_read_b128 v[222:225], v152 offset:64
	ds_read_b128 v[226:229], v152 offset:96
	ds_read_b128 v[230:233], v152 offset:128
	ds_read_b128 v[234:237], v152 offset:160
	ds_read_b128 v[238:241], v152 offset:192
	ds_read_b128 v[242:245], v152 offset:224
	s_or_b32 s12, s5, 31
	s_mov_b64 s[0:1], -1
	s_cmp_lt_i32 s12, s26
	s_waitcnt lgkmcnt(7)
	v_mfma_f32_32x32x16_bf16 v[80:95], v[2:5], v[96:99], 0
	s_waitcnt lgkmcnt(6)
	v_mfma_f32_32x32x16_bf16 v[80:95], v[6:9], v[100:103], v[80:95]
	s_waitcnt lgkmcnt(5)
	v_mfma_f32_32x32x16_bf16 v[80:95], v[222:225], v[104:107], v[80:95]
	s_waitcnt lgkmcnt(4)
	v_mfma_f32_32x32x16_bf16 v[80:95], v[226:229], v[108:111], v[80:95]
	s_waitcnt lgkmcnt(3)
	v_mfma_f32_32x32x16_bf16 v[80:95], v[230:233], v[112:115], v[80:95]
	s_waitcnt lgkmcnt(2)
	v_mfma_f32_32x32x16_bf16 v[80:95], v[234:237], v[116:119], v[80:95]
	s_waitcnt lgkmcnt(1)
	v_mfma_f32_32x32x16_bf16 v[80:95], v[238:241], v[120:123], v[80:95]
	s_waitcnt lgkmcnt(0)
	v_mfma_f32_32x32x16_bf16 v[80:95], v[242:245], v[124:127], v[80:95]
	s_nop 11
	v_mul_f32_e32 v209, 0x3e0293ee, v89
	v_mul_f32_e32 v152, 0x3e0293ee, v91
	v_mul_f32_e32 v208, 0x3e0293ee, v81
	v_mul_f32_e32 v1, 0x3e0293ee, v83
	s_cbranch_scc1 .LBB0_528
	v_and_b32_e32 v3, 64, v217
	v_xor_b32_e32 v2, 32, v217
	v_add_u32_e32 v3, 64, v3
	v_cmp_lt_i32_e32 vcc, v2, v3
	v_subrev_u32_e32 v83, s5, v185
	s_mov_b64 s[0:1], 0
	v_cndmask_b32_e32 v2, v217, v2, vcc
	v_lshlrev_b32_e32 v81, 2, v2
	v_mul_f32_e32 v2, 0x3e0293ee, v92
	v_exp_f32_e64 v3, -|v2|
	v_cmp_lt_f32_e32 vcc, 0, v2
	v_add_f32_e32 v4, 1.0, v3
	v_rcp_f32_e32 v4, v4
	s_nop 0
	v_mul_f32_e32 v3, v3, v4
	v_cndmask_b32_e32 v2, v3, v4, vcc
	v_cndmask_b32_e32 v3, v4, v3, vcc
	v_cmp_lt_i32_e32 vcc, v190, v83
	s_nop 1
	v_cndmask_b32_e32 v4, 1.0, v3, vcc
	v_mul_f32_e32 v3, 0x3e0293ee, v93
	v_exp_f32_e64 v5, -|v3|
	v_cndmask_b32_e32 v2, 0, v2, vcc
	v_cmp_lt_f32_e32 vcc, 0, v3
	v_mov_b32_e32 v3, s27
	v_add_f32_e32 v6, 1.0, v5
	v_rcp_f32_e32 v6, v6
	s_nop 0
	v_mul_f32_e32 v5, v5, v6
	v_cndmask_b32_e32 v7, v5, v6, vcc
	v_cndmask_b32_e32 v5, v6, v5, vcc
	v_cmp_lt_i32_e32 vcc, v191, v83
	s_nop 1
	v_cndmask_b32_e32 v6, 1.0, v5, vcc
	v_mul_f32_e32 v5, v4, v6
	v_mul_f32_e32 v4, 0x3e0293ee, v94
	v_cndmask_b32_e32 v3, v3, v7, vcc
	v_exp_f32_e64 v7, -|v4|
	v_cmp_lt_f32_e32 vcc, 0, v4
	v_mov_b32_e32 v4, s27
	v_add_f32_e32 v8, 1.0, v7
	v_rcp_f32_e32 v8, v8
	s_nop 0
	v_mul_f32_e32 v7, v7, v8
	v_cndmask_b32_e32 v9, v7, v8, vcc
	v_cndmask_b32_e32 v7, v8, v7, vcc
	v_cmp_lt_i32_e32 vcc, v192, v83
	s_nop 1
	v_cndmask_b32_e32 v7, 1.0, v7, vcc
	v_mul_f32_e32 v8, v7, v5
	v_mul_f32_e32 v5, 0x3e0293ee, v95
	v_cndmask_b32_e32 v4, v4, v9, vcc
	v_exp_f32_e64 v9, -|v5|
	v_cmp_lt_f32_e32 vcc, 0, v5
	v_mov_b32_e32 v5, s27
	v_add_f32_e32 v10, 1.0, v9
	v_rcp_f32_e32 v10, v10
	s_nop 0
	v_mul_f32_e32 v9, v9, v10
	v_cndmask_b32_e32 v11, v9, v10, vcc
	v_cndmask_b32_e32 v9, v10, v9, vcc
	v_cmp_lt_i32_e32 vcc, v193, v83
	s_nop 1
	v_cndmask_b32_e32 v10, 1.0, v9, vcc
	v_cndmask_b32_e32 v5, v5, v11, vcc
	v_mul_f32_e32 v11, v10, v8
	ds_bpermute_b32 v12, v81, v11
	s_waitcnt lgkmcnt(0)
	v_cndmask_b32_e64 v8, 1.0, v12, s[36:37]
	v_mul_f32_e32 v9, v153, v8
	v_mul_f32_e32 v8, v10, v9
	v_mul_f32_e32 v10, v11, v12
	v_mul_f32_e32 v89, v153, v10
	v_mul_f32_e32 v10, 0x3e0293ee, v88
	v_exp_f32_e64 v11, -|v10|
	v_cmp_lt_f32_e32 vcc, 0, v10
	v_mov_b32_e32 v10, s27
	v_mul_f32_e32 v7, v7, v8
	v_add_f32_e32 v12, 1.0, v11
	v_rcp_f32_e32 v12, v12
	v_mul_f32_e32 v6, v6, v7
	v_pk_mul_f32 v[2:3], v[2:3], v[6:7]
	v_pk_mul_f32 v[4:5], v[4:5], v[8:9]
	v_mul_f32_e32 v11, v11, v12
	v_cndmask_b32_e32 v13, v11, v12, vcc
	v_cndmask_b32_e32 v11, v12, v11, vcc
	v_cmp_lt_i32_e32 vcc, v194, v83
	s_nop 1
	v_cndmask_b32_e32 v12, 1.0, v11, vcc
	v_exp_f32_e64 v11, -|v209|
	v_cndmask_b32_e32 v10, v10, v13, vcc
	v_cmp_lt_f32_e32 vcc, 0, v209
	v_add_f32_e32 v13, 1.0, v11
	v_rcp_f32_e32 v13, v13
	s_nop 0
	v_mul_f32_e32 v11, v11, v13
	v_cndmask_b32_e32 v14, v11, v13, vcc
	v_cndmask_b32_e32 v13, v13, v11, vcc
	v_cmp_lt_i32_e32 vcc, v195, v83
	v_mov_b32_e32 v11, s27
	s_nop 0
	v_cndmask_b32_e32 v11, v11, v14, vcc
	v_cndmask_b32_e32 v14, 1.0, v13, vcc
	v_mul_f32_e32 v13, v12, v14
	v_mul_f32_e32 v12, 0x3e0293ee, v90
	v_exp_f32_e64 v15, -|v12|
	v_cmp_lt_f32_e32 vcc, 0, v12
	v_mov_b32_e32 v12, s27
	v_add_f32_e32 v91, 1.0, v15
	v_rcp_f32_e32 v91, v91
	s_nop 0
	v_mul_f32_e32 v15, v15, v91
	v_cndmask_b32_e32 v154, v15, v91, vcc
	v_cndmask_b32_e32 v15, v91, v15, vcc
	v_cmp_lt_i32_e32 vcc, v196, v83
	s_nop 1
	v_cndmask_b32_e32 v15, 1.0, v15, vcc
	v_mul_f32_e32 v91, v15, v13
	v_exp_f32_e64 v13, -|v152|
	v_cndmask_b32_e32 v12, v12, v154, vcc
	v_cmp_lt_f32_e32 vcc, 0, v152
	v_add_f32_e32 v154, 1.0, v13
	v_rcp_f32_e32 v154, v154
	s_nop 0
	v_mul_f32_e32 v13, v13, v154
	v_cndmask_b32_e32 v155, v13, v154, vcc
	v_cndmask_b32_e32 v154, v154, v13, vcc
	v_cmp_lt_i32_e32 vcc, v197, v83
	v_mov_b32_e32 v13, s27
	s_nop 0
	v_cndmask_b32_e32 v154, 1.0, v154, vcc
	v_mul_f32_e32 v91, v154, v91
	ds_bpermute_b32 v156, v81, v91
	v_cndmask_b32_e32 v13, v13, v155, vcc
	s_waitcnt lgkmcnt(0)
	v_cndmask_b32_e64 v155, 1.0, v156, s[36:37]
	v_mul_f32_e32 v91, v91, v156
	v_mul_f32_e32 v155, v89, v155
	v_mul_f32_e32 v91, v91, v89
	v_mul_f32_e32 v89, 0x3e0293ee, v84
	v_exp_f32_e64 v156, -|v89|
	v_cmp_lt_f32_e32 vcc, 0, v89
	v_mul_f32_e32 v154, v154, v155
	v_mul_f32_e32 v15, v15, v154
	v_add_f32_e32 v157, 1.0, v156
	v_rcp_f32_e32 v157, v157
	v_mul_f32_e32 v14, v14, v15
	v_pk_mul_f32 v[12:13], v[12:13], v[154:155]
	v_pk_mul_f32 v[10:11], v[10:11], v[14:15]
	v_mul_f32_e32 v156, v156, v157
	v_cndmask_b32_e32 v89, v156, v157, vcc
	v_cndmask_b32_e32 v157, v157, v156, vcc
	v_cmp_lt_i32_e32 vcc, v198, v83
	v_mov_b32_e32 v156, s27
	s_nop 0
	v_cndmask_b32_e32 v156, v156, v89, vcc
	v_mul_f32_e32 v89, 0x3e0293ee, v85
	v_cndmask_b32_e32 v158, 1.0, v157, vcc
	v_exp_f32_e64 v157, -|v89|
	v_cmp_lt_f32_e32 vcc, 0, v89
	v_mov_b32_e32 v89, s27
	v_add_f32_e32 v159, 1.0, v157
	v_rcp_f32_e32 v159, v159
	s_nop 0
	v_mul_f32_e32 v157, v157, v159
	v_cndmask_b32_e32 v160, v157, v159, vcc
	v_cndmask_b32_e32 v159, v159, v157, vcc
	v_cmp_lt_i32_e32 vcc, v199, v83
	s_nop 1
	v_cndmask_b32_e32 v157, v89, v160, vcc
	v_cndmask_b32_e32 v160, 1.0, v159, vcc
	v_mul_f32_e32 v89, v158, v160
	v_mul_f32_e32 v158, 0x3e0293ee, v86
	v_exp_f32_e64 v159, -|v158|
	v_cmp_lt_f32_e32 vcc, 0, v158
	v_mov_b32_e32 v158, s27
	v_add_f32_e32 v161, 1.0, v159
	v_rcp_f32_e32 v161, v161
	s_nop 0
	v_mul_f32_e32 v159, v159, v161
	v_cndmask_b32_e32 v162, v159, v161, vcc
	v_cndmask_b32_e32 v159, v161, v159, vcc
	v_cmp_lt_i32_e32 vcc, v200, v83
	s_nop 1
	v_cndmask_b32_e32 v161, 1.0, v159, vcc
	v_cndmask_b32_e32 v158, v158, v162, vcc
	v_mul_f32_e32 v162, v161, v89
	v_mul_f32_e32 v89, 0x3e0293ee, v87
	v_exp_f32_e64 v159, -|v89|
	v_cmp_lt_f32_e32 vcc, 0, v89
	v_mov_b32_e32 v89, s27
	v_add_f32_e32 v163, 1.0, v159
	v_rcp_f32_e32 v163, v163
	s_nop 0
	v_mul_f32_e32 v159, v159, v163
	v_cndmask_b32_e32 v164, v159, v163, vcc
	v_cndmask_b32_e32 v163, v163, v159, vcc
	v_cmp_lt_i32_e32 vcc, v201, v83
	s_nop 1
	v_cndmask_b32_e32 v159, v89, v164, vcc
	v_cndmask_b32_e32 v89, 1.0, v163, vcc
	v_mul_f32_e32 v164, v89, v162
	ds_bpermute_b32 v165, v81, v164
	s_waitcnt lgkmcnt(0)
	v_cndmask_b32_e64 v162, 1.0, v165, s[36:37]
	v_mul_f32_e32 v163, v91, v162
	v_mul_f32_e32 v162, v89, v163
	v_mul_f32_e32 v89, v164, v165
	v_mul_f32_e32 v91, v89, v91
	v_mul_f32_e32 v89, 0x3e0293ee, v80
	v_exp_f32_e64 v164, -|v89|
	v_cmp_lt_f32_e32 vcc, 0, v89
	v_mul_f32_e32 v161, v161, v162
	v_mul_f32_e32 v160, v160, v161
	v_add_f32_e32 v165, 1.0, v164
	v_rcp_f32_e32 v165, v165
	v_pk_mul_f32 v[158:159], v[158:159], v[162:163]
	v_pk_mul_f32 v[156:157], v[156:157], v[160:161]
	v_mul_f32_e32 v164, v164, v165
	v_cndmask_b32_e32 v89, v164, v165, vcc
	v_cndmask_b32_e32 v165, v165, v164, vcc
	v_cmp_lt_i32_e32 vcc, v186, v83
	v_mov_b32_e32 v164, s27
	s_nop 0
	v_cndmask_b32_e32 v164, v164, v89, vcc
	v_exp_f32_e64 v89, -|v208|
	v_cndmask_b32_e32 v178, 1.0, v165, vcc
	v_cmp_lt_f32_e32 vcc, 0, v208
	v_add_f32_e32 v165, 1.0, v89
	v_rcp_f32_e32 v165, v165
	s_nop 0
	v_mul_f32_e32 v89, v89, v165
	v_cndmask_b32_e32 v179, v89, v165, vcc
	v_cndmask_b32_e32 v222, v165, v89, vcc
	v_cmp_lt_i32_e32 vcc, v202, v83
	v_mov_b32_e32 v89, s27
	s_nop 0
	v_cndmask_b32_e32 v165, v89, v179, vcc
	v_cndmask_b32_e32 v89, 1.0, v222, vcc
	v_mul_f32_e32 v179, v178, v89
	v_mul_f32_e32 v178, 0x3e0293ee, v82
	v_exp_f32_e64 v222, -|v178|
	v_cmp_lt_f32_e32 vcc, 0, v178
	v_mov_b32_e32 v178, s27
	v_add_f32_e32 v223, 1.0, v222
	v_rcp_f32_e32 v223, v223
	s_nop 0
	v_mul_f32_e32 v222, v222, v223
	v_cndmask_b32_e32 v224, v222, v223, vcc
	v_cndmask_b32_e32 v222, v223, v222, vcc
	v_cmp_lt_i32_e32 vcc, v203, v83
	s_nop 1
	v_cndmask_b32_e32 v178, v178, v224, vcc
	v_cndmask_b32_e32 v224, 1.0, v222, vcc
	v_mul_f32_e32 v222, v224, v179
	v_exp_f32_e64 v179, -|v1|
	v_cmp_lt_f32_e32 vcc, 0, v1
	v_add_f32_e32 v223, 1.0, v179
	v_rcp_f32_e32 v223, v223
	s_nop 0
	v_mul_f32_e32 v179, v179, v223
	v_cndmask_b32_e32 v225, v179, v223, vcc
	v_cndmask_b32_e32 v223, v223, v179, vcc
	v_cmp_lt_i32_e32 vcc, v204, v83
	v_mov_b32_e32 v83, s27
	s_nop 0
	v_cndmask_b32_e32 v179, v83, v225, vcc
	v_cndmask_b32_e32 v83, 1.0, v223, vcc
	v_mul_f32_e32 v226, v83, v222
	ds_bpermute_b32 v81, v81, v226
	s_waitcnt lgkmcnt(0)
	v_cndmask_b32_e64 v222, 1.0, v81, s[36:37]
	v_mul_f32_e32 v223, v91, v222
	v_mul_f32_e32 v222, v83, v223
	v_mul_f32_e32 v225, v224, v222
	v_mul_f32_e32 v224, v89, v225
	v_mul_f32_e32 v6, v226, v81
	v_pk_mul_f32 v[178:179], v[178:179], v[222:223]
	v_pk_mul_f32 v[164:165], v[164:165], v[224:225]
	v_mul_f32_e32 v6, v6, v91

.LBB0_530:
	v_add_u32_e32 v1, v207, v189
	v_cvt_pk_bf16_f32 v8, v10, v11
	v_cvt_pk_bf16_f32 v10, v2, v3
	v_cvt_pk_bf16_f32 v11, v4, v5
	ds_read_b64_tr_b16 v[222:223], v1 offset:34816
	ds_read_b64_tr_b16 v[224:225], v1 offset:37376
	ds_read_b64_tr_b16 v[226:227], v1 offset:39936
	ds_read_b64_tr_b16 v[228:229], v1 offset:42496
	ds_read_b64_tr_b16 v[230:231], v1 offset:34880
	ds_read_b64_tr_b16 v[232:233], v1 offset:37440
	ds_read_b64_tr_b16 v[234:235], v1 offset:40000
	ds_read_b64_tr_b16 v[236:237], v1 offset:42560
	ds_read_b64_tr_b16 v[238:239], v1 offset:34944
	ds_read_b64_tr_b16 v[240:241], v1 offset:37504
	ds_read_b64_tr_b16 v[242:243], v1 offset:40064
	ds_read_b64_tr_b16 v[244:245], v1 offset:42624
	v_cvt_pk_bf16_f32 v80, v164, v165
	v_cvt_pk_bf16_f32 v81, v178, v179
	v_cvt_pk_bf16_f32 v82, v156, v157
	v_cvt_pk_bf16_f32 v83, v158, v159
	v_cvt_pk_bf16_f32 v9, v12, v13
	v_mov_b32_e32 v153, v6
	s_waitcnt lgkmcnt(10)
	v_mfma_f32_32x32x16_bf16 v[16:31], v[222:225], v[80:83], v[16:31]
	ds_read_b64_tr_b16 v[84:85], v1 offset:35008
	ds_read_b64_tr_b16 v[86:87], v1 offset:37568
	s_waitcnt lgkmcnt(10)
	v_mfma_f32_32x32x16_bf16 v[16:31], v[226:229], v[8:11], v[16:31]
	ds_read_b64_tr_b16 v[88:89], v1 offset:40128
	ds_read_b64_tr_b16 v[90:91], v1 offset:42688
	s_waitcnt lgkmcnt(10)
	v_mfma_f32_32x32x16_bf16 v[32:47], v[230:233], v[80:83], v[32:47]
	s_waitcnt lgkmcnt(8)
	v_mfma_f32_32x32x16_bf16 v[32:47], v[234:237], v[8:11], v[32:47]
	s_waitcnt lgkmcnt(6)
	v_mfma_f32_32x32x16_bf16 v[48:63], v[238:241], v[80:83], v[48:63]
	s_waitcnt lgkmcnt(4)
	v_mfma_f32_32x32x16_bf16 v[48:63], v[242:245], v[8:11], v[48:63]
	s_waitcnt lgkmcnt(2)
	v_mfma_f32_32x32x16_bf16 v[64:79], v[84:87], v[80:83], v[64:79]
	s_waitcnt lgkmcnt(0)
	v_mfma_f32_32x32x16_bf16 v[64:79], v[88:91], v[8:11], v[64:79]

.LBB0_539:
	s_cmp_gt_i32 s84, s3
	s_cselect_b64 s[0:1], -1, 0
	s_or_b64 s[0:1], s[50:51], s[0:1]
	s_and_b64 vcc, exec, s[0:1]
	s_cbranch_vccnz .LBB0_553
	v_add3_u32 v205, s28, v187, v188
	s_or_b32 s28, s84, 32
	s_cmp_gt_i32 s28, s3
	v_add_u32_e32 v206, s21, v180
	s_cbranch_scc1 .LBB0_547
	v_cmp_gt_f32_e32 vcc, s86, v153
	s_cmp_eq_u64 vcc, -1
	s_cbranch_scc1 .LBB0_547
	v_add_u32_e32 v10, v206, v1
	ds_read_b128 v[2:5], v10 offset:8704
	ds_read_b128 v[6:9], v10 offset:8736
	ds_read_b128 v[222:225], v10 offset:8768
	ds_read_b128 v[226:229], v10 offset:8800
	ds_read_b128 v[230:233], v10 offset:8832
	ds_read_b128 v[234:237], v10 offset:8864
	ds_read_b128 v[238:241], v10 offset:8896
	ds_read_b128 v[242:245], v10 offset:8928
	s_or_b32 s12, s84, 63
	s_mov_b64 s[0:1], -1
	s_cmp_lt_i32 s12, s26
	s_waitcnt lgkmcnt(7)
	v_mfma_f32_32x32x16_bf16 v[80:95], v[2:5], v[96:99], 0
	s_waitcnt lgkmcnt(6)
	v_mfma_f32_32x32x16_bf16 v[80:95], v[6:9], v[100:103], v[80:95]
	s_waitcnt lgkmcnt(5)
	v_mfma_f32_32x32x16_bf16 v[80:95], v[222:225], v[104:107], v[80:95]
	s_waitcnt lgkmcnt(4)
	v_mfma_f32_32x32x16_bf16 v[80:95], v[226:229], v[108:111], v[80:95]
	s_waitcnt lgkmcnt(3)
	v_mfma_f32_32x32x16_bf16 v[80:95], v[230:233], v[112:115], v[80:95]
	s_waitcnt lgkmcnt(2)
	v_mfma_f32_32x32x16_bf16 v[80:95], v[234:237], v[116:119], v[80:95]
	s_waitcnt lgkmcnt(1)
	v_mfma_f32_32x32x16_bf16 v[80:95], v[238:241], v[120:123], v[80:95]
	s_waitcnt lgkmcnt(0)
	v_mfma_f32_32x32x16_bf16 v[80:95], v[242:245], v[124:127], v[80:95]
	s_nop 11
	v_mul_f32_e32 v209, 0x3e0293ee, v89
	v_mul_f32_e32 v152, 0x3e0293ee, v91
	v_mul_f32_e32 v208, 0x3e0293ee, v81
	v_mul_f32_e32 v207, 0x3e0293ee, v83
	s_cbranch_scc1 .LBB0_544
	v_and_b32_e32 v3, 64, v217
	v_xor_b32_e32 v2, 32, v217
	v_add_u32_e32 v3, 64, v3
	v_cmp_lt_i32_e32 vcc, v2, v3
	v_subrev_u32_e32 v83, s28, v185
	s_mov_b64 s[0:1], 0
	v_cndmask_b32_e32 v2, v217, v2, vcc
	v_lshlrev_b32_e32 v81, 2, v2
	v_mul_f32_e32 v2, 0x3e0293ee, v92
	v_exp_f32_e64 v3, -|v2|
	v_cmp_lt_f32_e32 vcc, 0, v2
	v_add_f32_e32 v4, 1.0, v3
	v_rcp_f32_e32 v4, v4
	s_nop 0
	v_mul_f32_e32 v3, v3, v4
	v_cndmask_b32_e32 v2, v3, v4, vcc
	v_cndmask_b32_e32 v3, v4, v3, vcc
	v_cmp_lt_i32_e32 vcc, v190, v83
	s_nop 1
	v_cndmask_b32_e32 v4, 1.0, v3, vcc
	v_mul_f32_e32 v3, 0x3e0293ee, v93
	v_exp_f32_e64 v5, -|v3|
	v_cndmask_b32_e32 v2, 0, v2, vcc
	v_cmp_lt_f32_e32 vcc, 0, v3
	v_mov_b32_e32 v3, s27
	v_add_f32_e32 v6, 1.0, v5
	v_rcp_f32_e32 v6, v6
	s_nop 0
	v_mul_f32_e32 v5, v5, v6
	v_cndmask_b32_e32 v7, v5, v6, vcc
	v_cndmask_b32_e32 v5, v6, v5, vcc
	v_cmp_lt_i32_e32 vcc, v191, v83
	s_nop 1
	v_cndmask_b32_e32 v6, 1.0, v5, vcc
	v_mul_f32_e32 v5, v4, v6
	v_mul_f32_e32 v4, 0x3e0293ee, v94
	v_cndmask_b32_e32 v3, v3, v7, vcc
	v_exp_f32_e64 v7, -|v4|
	v_cmp_lt_f32_e32 vcc, 0, v4
	v_mov_b32_e32 v4, s27
	v_add_f32_e32 v8, 1.0, v7
	v_rcp_f32_e32 v8, v8
	s_nop 0
	v_mul_f32_e32 v7, v7, v8
	v_cndmask_b32_e32 v9, v7, v8, vcc
	v_cndmask_b32_e32 v7, v8, v7, vcc
	v_cmp_lt_i32_e32 vcc, v192, v83
	s_nop 1
	v_cndmask_b32_e32 v7, 1.0, v7, vcc
	v_mul_f32_e32 v8, v7, v5
	v_mul_f32_e32 v5, 0x3e0293ee, v95
	v_cndmask_b32_e32 v4, v4, v9, vcc
	v_exp_f32_e64 v9, -|v5|
	v_cmp_lt_f32_e32 vcc, 0, v5
	v_mov_b32_e32 v5, s27
	v_add_f32_e32 v10, 1.0, v9
	v_rcp_f32_e32 v10, v10
	s_nop 0
	v_mul_f32_e32 v9, v9, v10
	v_cndmask_b32_e32 v11, v9, v10, vcc
	v_cndmask_b32_e32 v9, v10, v9, vcc
	v_cmp_lt_i32_e32 vcc, v193, v83
	s_nop 1
	v_cndmask_b32_e32 v10, 1.0, v9, vcc
	v_cndmask_b32_e32 v5, v5, v11, vcc
	v_mul_f32_e32 v11, v10, v8
	ds_bpermute_b32 v12, v81, v11
	s_waitcnt lgkmcnt(0)
	v_cndmask_b32_e64 v8, 1.0, v12, s[36:37]
	v_mul_f32_e32 v9, v153, v8
	v_mul_f32_e32 v8, v10, v9
	v_mul_f32_e32 v10, v11, v12
	v_mul_f32_e32 v89, v153, v10
	v_mul_f32_e32 v10, 0x3e0293ee, v88
	v_exp_f32_e64 v11, -|v10|
	v_cmp_lt_f32_e32 vcc, 0, v10
	v_mov_b32_e32 v10, s27
	v_mul_f32_e32 v7, v7, v8
	v_add_f32_e32 v12, 1.0, v11
	v_rcp_f32_e32 v12, v12
	v_mul_f32_e32 v6, v6, v7
	v_pk_mul_f32 v[2:3], v[2:3], v[6:7]
	v_pk_mul_f32 v[4:5], v[4:5], v[8:9]
	v_mul_f32_e32 v11, v11, v12
	v_cndmask_b32_e32 v13, v11, v12, vcc
	v_cndmask_b32_e32 v11, v12, v11, vcc
	v_cmp_lt_i32_e32 vcc, v194, v83
	s_nop 1
	v_cndmask_b32_e32 v12, 1.0, v11, vcc
	v_exp_f32_e64 v11, -|v209|
	v_cndmask_b32_e32 v10, v10, v13, vcc
	v_cmp_lt_f32_e32 vcc, 0, v209
	v_add_f32_e32 v13, 1.0, v11
	v_rcp_f32_e32 v13, v13
	s_nop 0
	v_mul_f32_e32 v11, v11, v13
	v_cndmask_b32_e32 v14, v11, v13, vcc
	v_cndmask_b32_e32 v13, v13, v11, vcc
	v_cmp_lt_i32_e32 vcc, v195, v83
	v_mov_b32_e32 v11, s27
	s_nop 0
	v_cndmask_b32_e32 v11, v11, v14, vcc
	v_cndmask_b32_e32 v14, 1.0, v13, vcc
	v_mul_f32_e32 v13, v12, v14
	v_mul_f32_e32 v12, 0x3e0293ee, v90
	v_exp_f32_e64 v15, -|v12|
	v_cmp_lt_f32_e32 vcc, 0, v12
	v_mov_b32_e32 v12, s27
	v_add_f32_e32 v91, 1.0, v15
	v_rcp_f32_e32 v91, v91
	s_nop 0
	v_mul_f32_e32 v15, v15, v91
	v_cndmask_b32_e32 v154, v15, v91, vcc
	v_cndmask_b32_e32 v15, v91, v15, vcc
	v_cmp_lt_i32_e32 vcc, v196, v83
	s_nop 1
	v_cndmask_b32_e32 v15, 1.0, v15, vcc
	v_mul_f32_e32 v91, v15, v13
	v_exp_f32_e64 v13, -|v152|
	v_cndmask_b32_e32 v12, v12, v154, vcc
	v_cmp_lt_f32_e32 vcc, 0, v152
	v_add_f32_e32 v154, 1.0, v13
	v_rcp_f32_e32 v154, v154
	s_nop 0
	v_mul_f32_e32 v13, v13, v154
	v_cndmask_b32_e32 v155, v13, v154, vcc
	v_cndmask_b32_e32 v154, v154, v13, vcc
	v_cmp_lt_i32_e32 vcc, v197, v83
	v_mov_b32_e32 v13, s27
	s_nop 0
	v_cndmask_b32_e32 v154, 1.0, v154, vcc
	v_mul_f32_e32 v91, v154, v91
	ds_bpermute_b32 v156, v81, v91
	v_cndmask_b32_e32 v13, v13, v155, vcc
	s_waitcnt lgkmcnt(0)
	v_cndmask_b32_e64 v155, 1.0, v156, s[36:37]
	v_mul_f32_e32 v91, v91, v156
	v_mul_f32_e32 v155, v89, v155
	v_mul_f32_e32 v91, v91, v89
	v_mul_f32_e32 v89, 0x3e0293ee, v84
	v_exp_f32_e64 v156, -|v89|
	v_cmp_lt_f32_e32 vcc, 0, v89
	v_mul_f32_e32 v154, v154, v155
	v_mul_f32_e32 v15, v15, v154
	v_add_f32_e32 v157, 1.0, v156
	v_rcp_f32_e32 v157, v157
	v_mul_f32_e32 v14, v14, v15
	v_pk_mul_f32 v[12:13], v[12:13], v[154:155]
	v_pk_mul_f32 v[10:11], v[10:11], v[14:15]
	v_mul_f32_e32 v156, v156, v157
	v_cndmask_b32_e32 v89, v156, v157, vcc
	v_cndmask_b32_e32 v157, v157, v156, vcc
	v_cmp_lt_i32_e32 vcc, v198, v83
	v_mov_b32_e32 v156, s27
	s_nop 0
	v_cndmask_b32_e32 v156, v156, v89, vcc
	v_mul_f32_e32 v89, 0x3e0293ee, v85
	v_cndmask_b32_e32 v158, 1.0, v157, vcc
	v_exp_f32_e64 v157, -|v89|
	v_cmp_lt_f32_e32 vcc, 0, v89
	v_mov_b32_e32 v89, s27
	v_add_f32_e32 v159, 1.0, v157
	v_rcp_f32_e32 v159, v159
	s_nop 0
	v_mul_f32_e32 v157, v157, v159
	v_cndmask_b32_e32 v160, v157, v159, vcc
	v_cndmask_b32_e32 v159, v159, v157, vcc
	v_cmp_lt_i32_e32 vcc, v199, v83
	s_nop 1
	v_cndmask_b32_e32 v157, v89, v160, vcc
	v_cndmask_b32_e32 v160, 1.0, v159, vcc
	v_mul_f32_e32 v89, v158, v160
	v_mul_f32_e32 v158, 0x3e0293ee, v86
	v_exp_f32_e64 v159, -|v158|
	v_cmp_lt_f32_e32 vcc, 0, v158
	v_mov_b32_e32 v158, s27
	v_add_f32_e32 v161, 1.0, v159
	v_rcp_f32_e32 v161, v161
	s_nop 0
	v_mul_f32_e32 v159, v159, v161
	v_cndmask_b32_e32 v162, v159, v161, vcc
	v_cndmask_b32_e32 v159, v161, v159, vcc
	v_cmp_lt_i32_e32 vcc, v200, v83
	s_nop 1
	v_cndmask_b32_e32 v161, 1.0, v159, vcc
	v_cndmask_b32_e32 v158, v158, v162, vcc
	v_mul_f32_e32 v162, v161, v89
	v_mul_f32_e32 v89, 0x3e0293ee, v87
	v_exp_f32_e64 v159, -|v89|
	v_cmp_lt_f32_e32 vcc, 0, v89
	v_mov_b32_e32 v89, s27
	v_add_f32_e32 v163, 1.0, v159
	v_rcp_f32_e32 v163, v163
	s_nop 0
	v_mul_f32_e32 v159, v159, v163
	v_cndmask_b32_e32 v164, v159, v163, vcc
	v_cndmask_b32_e32 v163, v163, v159, vcc
	v_cmp_lt_i32_e32 vcc, v201, v83
	s_nop 1
	v_cndmask_b32_e32 v159, v89, v164, vcc
	v_cndmask_b32_e32 v89, 1.0, v163, vcc
	v_mul_f32_e32 v164, v89, v162
	ds_bpermute_b32 v165, v81, v164
	s_waitcnt lgkmcnt(0)
	v_cndmask_b32_e64 v162, 1.0, v165, s[36:37]
	v_mul_f32_e32 v163, v91, v162
	v_mul_f32_e32 v162, v89, v163
	v_mul_f32_e32 v89, v164, v165
	v_mul_f32_e32 v91, v89, v91
	v_mul_f32_e32 v89, 0x3e0293ee, v80
	v_exp_f32_e64 v164, -|v89|
	v_cmp_lt_f32_e32 vcc, 0, v89
	v_mul_f32_e32 v161, v161, v162
	v_mul_f32_e32 v160, v160, v161
	v_add_f32_e32 v165, 1.0, v164
	v_rcp_f32_e32 v165, v165
	v_pk_mul_f32 v[158:159], v[158:159], v[162:163]
	v_pk_mul_f32 v[156:157], v[156:157], v[160:161]
	v_mul_f32_e32 v164, v164, v165
	v_cndmask_b32_e32 v89, v164, v165, vcc
	v_cndmask_b32_e32 v165, v165, v164, vcc
	v_cmp_lt_i32_e32 vcc, v186, v83
	v_mov_b32_e32 v164, s27
	s_nop 0
	v_cndmask_b32_e32 v164, v164, v89, vcc
	v_exp_f32_e64 v89, -|v208|
	v_cndmask_b32_e32 v178, 1.0, v165, vcc
	v_cmp_lt_f32_e32 vcc, 0, v208
	v_add_f32_e32 v165, 1.0, v89
	v_rcp_f32_e32 v165, v165
	s_nop 0
	v_mul_f32_e32 v89, v89, v165
	v_cndmask_b32_e32 v179, v89, v165, vcc
	v_cndmask_b32_e32 v222, v165, v89, vcc
	v_cmp_lt_i32_e32 vcc, v202, v83
	v_mov_b32_e32 v89, s27
	s_nop 0
	v_cndmask_b32_e32 v165, v89, v179, vcc
	v_cndmask_b32_e32 v89, 1.0, v222, vcc
	v_mul_f32_e32 v179, v178, v89
	v_mul_f32_e32 v178, 0x3e0293ee, v82
	v_exp_f32_e64 v222, -|v178|
	v_cmp_lt_f32_e32 vcc, 0, v178
	v_mov_b32_e32 v178, s27
	v_add_f32_e32 v223, 1.0, v222
	v_rcp_f32_e32 v223, v223
	s_nop 0
	v_mul_f32_e32 v222, v222, v223
	v_cndmask_b32_e32 v224, v222, v223, vcc
	v_cndmask_b32_e32 v222, v223, v222, vcc
	v_cmp_lt_i32_e32 vcc, v203, v83
	s_nop 1
	v_cndmask_b32_e32 v178, v178, v224, vcc
	v_cndmask_b32_e32 v224, 1.0, v222, vcc
	v_mul_f32_e32 v222, v224, v179
	v_exp_f32_e64 v179, -|v207|
	v_cmp_lt_f32_e32 vcc, 0, v207
	v_add_f32_e32 v223, 1.0, v179
	v_rcp_f32_e32 v223, v223
	s_nop 0
	v_mul_f32_e32 v179, v179, v223
	v_cndmask_b32_e32 v225, v179, v223, vcc
	v_cndmask_b32_e32 v223, v223, v179, vcc
	v_cmp_lt_i32_e32 vcc, v204, v83
	v_mov_b32_e32 v83, s27
	s_nop 0
	v_cndmask_b32_e32 v179, v83, v225, vcc
	v_cndmask_b32_e32 v83, 1.0, v223, vcc
	v_mul_f32_e32 v226, v83, v222
	ds_bpermute_b32 v81, v81, v226
	s_waitcnt lgkmcnt(0)
	v_cndmask_b32_e64 v222, 1.0, v81, s[36:37]
	v_mul_f32_e32 v223, v91, v222
	v_mul_f32_e32 v222, v83, v223
	v_mul_f32_e32 v225, v224, v222
	v_mul_f32_e32 v224, v89, v225
	v_mul_f32_e32 v6, v226, v81
	v_pk_mul_f32 v[178:179], v[178:179], v[222:223]
	v_pk_mul_f32 v[164:165], v[164:165], v[224:225]
	v_mul_f32_e32 v6, v6, v91

.LBB0_546:
	v_add_u32_e32 v7, v205, v189
	v_cvt_pk_bf16_f32 v8, v10, v11
	v_cvt_pk_bf16_f32 v10, v2, v3
	v_cvt_pk_bf16_f32 v11, v4, v5
	ds_read_b64_tr_b16 v[222:223], v7 offset:45056
	ds_read_b64_tr_b16 v[224:225], v7 offset:47616
	ds_read_b64_tr_b16 v[226:227], v7 offset:50176
	ds_read_b64_tr_b16 v[228:229], v7 offset:52736
	ds_read_b64_tr_b16 v[230:231], v7 offset:45120
	ds_read_b64_tr_b16 v[232:233], v7 offset:47680
	ds_read_b64_tr_b16 v[234:235], v7 offset:50240
	ds_read_b64_tr_b16 v[236:237], v7 offset:52800
	ds_read_b64_tr_b16 v[238:239], v7 offset:45184
	ds_read_b64_tr_b16 v[240:241], v7 offset:47744
	ds_read_b64_tr_b16 v[242:243], v7 offset:50304
	ds_read_b64_tr_b16 v[244:245], v7 offset:52864
	v_cvt_pk_bf16_f32 v80, v164, v165
	v_cvt_pk_bf16_f32 v81, v178, v179
	v_cvt_pk_bf16_f32 v82, v156, v157
	v_cvt_pk_bf16_f32 v83, v158, v159
	v_cvt_pk_bf16_f32 v9, v12, v13
	v_mov_b32_e32 v153, v6
	s_waitcnt lgkmcnt(10)
	v_mfma_f32_32x32x16_bf16 v[16:31], v[222:225], v[80:83], v[16:31]
	ds_read_b64_tr_b16 v[84:85], v7 offset:45248
	ds_read_b64_tr_b16 v[86:87], v7 offset:47808
	s_waitcnt lgkmcnt(10)
	v_mfma_f32_32x32x16_bf16 v[16:31], v[226:229], v[8:11], v[16:31]
	ds_read_b64_tr_b16 v[88:89], v7 offset:50368
	ds_read_b64_tr_b16 v[90:91], v7 offset:52928
	s_waitcnt lgkmcnt(10)
	v_mfma_f32_32x32x16_bf16 v[32:47], v[230:233], v[80:83], v[32:47]
	s_waitcnt lgkmcnt(8)
	v_mfma_f32_32x32x16_bf16 v[32:47], v[234:237], v[8:11], v[32:47]
	s_waitcnt lgkmcnt(6)
	v_mfma_f32_32x32x16_bf16 v[48:63], v[238:241], v[80:83], v[48:63]
	s_waitcnt lgkmcnt(4)
	v_mfma_f32_32x32x16_bf16 v[48:63], v[242:245], v[8:11], v[48:63]
	s_waitcnt lgkmcnt(2)
	v_mfma_f32_32x32x16_bf16 v[64:79], v[84:87], v[80:83], v[64:79]
	s_waitcnt lgkmcnt(0)
	v_mfma_f32_32x32x16_bf16 v[64:79], v[88:91], v[8:11], v[64:79]
.LBB0_547:
	v_cmp_gt_f32_e32 vcc, s86, v153
	s_cmp_eq_u64 vcc, -1
	s_cbranch_scc1 .LBB0_553
	v_add_u32_e32 v10, v206, v1
	ds_read_b128 v[2:5], v10
	ds_read_b128 v[6:9], v10 offset:32
	ds_read_b128 v[222:225], v10 offset:64
	ds_read_b128 v[226:229], v10 offset:96
	ds_read_b128 v[230:233], v10 offset:128
	ds_read_b128 v[234:237], v10 offset:160
	ds_read_b128 v[238:241], v10 offset:192
	ds_read_b128 v[242:245], v10 offset:224
	s_or_b32 s12, s84, 31
	s_mov_b64 s[0:1], -1
	s_cmp_lt_i32 s12, s26
	s_waitcnt lgkmcnt(7)
	v_mfma_f32_32x32x16_bf16 v[80:95], v[2:5], v[96:99], 0
	s_waitcnt lgkmcnt(6)
	v_mfma_f32_32x32x16_bf16 v[80:95], v[6:9], v[100:103], v[80:95]
	s_waitcnt lgkmcnt(5)
	v_mfma_f32_32x32x16_bf16 v[80:95], v[222:225], v[104:107], v[80:95]
	s_waitcnt lgkmcnt(4)
	v_mfma_f32_32x32x16_bf16 v[80:95], v[226:229], v[108:111], v[80:95]
	s_waitcnt lgkmcnt(3)
	v_mfma_f32_32x32x16_bf16 v[80:95], v[230:233], v[112:115], v[80:95]
	s_waitcnt lgkmcnt(2)
	v_mfma_f32_32x32x16_bf16 v[80:95], v[234:237], v[116:119], v[80:95]
	s_waitcnt lgkmcnt(1)
	v_mfma_f32_32x32x16_bf16 v[80:95], v[238:241], v[120:123], v[80:95]
	s_waitcnt lgkmcnt(0)
	v_mfma_f32_32x32x16_bf16 v[80:95], v[242:245], v[124:127], v[80:95]
	s_nop 11
	v_mul_f32_e32 v208, 0x3e0293ee, v89
	v_mul_f32_e32 v152, 0x3e0293ee, v91
	v_mul_f32_e32 v207, 0x3e0293ee, v81
	v_mul_f32_e32 v206, 0x3e0293ee, v83
	s_cbranch_scc1 .LBB0_550
	v_and_b32_e32 v3, 64, v217
	v_xor_b32_e32 v2, 32, v217
	v_add_u32_e32 v3, 64, v3
	v_cmp_lt_i32_e32 vcc, v2, v3
	v_subrev_u32_e32 v83, s84, v185
	s_mov_b64 s[0:1], 0
	v_cndmask_b32_e32 v2, v217, v2, vcc
	v_lshlrev_b32_e32 v81, 2, v2
	v_mul_f32_e32 v2, 0x3e0293ee, v92
	v_exp_f32_e64 v3, -|v2|
	v_cmp_lt_f32_e32 vcc, 0, v2
	v_add_f32_e32 v4, 1.0, v3
	v_rcp_f32_e32 v4, v4
	s_nop 0
	v_mul_f32_e32 v3, v3, v4
	v_cndmask_b32_e32 v2, v3, v4, vcc
	v_cndmask_b32_e32 v3, v4, v3, vcc
	v_cmp_lt_i32_e32 vcc, v190, v83
	s_nop 1
	v_cndmask_b32_e32 v4, 1.0, v3, vcc
	v_mul_f32_e32 v3, 0x3e0293ee, v93
	v_exp_f32_e64 v5, -|v3|
	v_cndmask_b32_e32 v2, 0, v2, vcc
	v_cmp_lt_f32_e32 vcc, 0, v3
	v_mov_b32_e32 v3, s27
	v_add_f32_e32 v6, 1.0, v5
	v_rcp_f32_e32 v6, v6
	s_nop 0
	v_mul_f32_e32 v5, v5, v6
	v_cndmask_b32_e32 v7, v5, v6, vcc
	v_cndmask_b32_e32 v5, v6, v5, vcc
	v_cmp_lt_i32_e32 vcc, v191, v83
	s_nop 1
	v_cndmask_b32_e32 v6, 1.0, v5, vcc
	v_mul_f32_e32 v5, v4, v6
	v_mul_f32_e32 v4, 0x3e0293ee, v94
	v_cndmask_b32_e32 v3, v3, v7, vcc
	v_exp_f32_e64 v7, -|v4|
	v_cmp_lt_f32_e32 vcc, 0, v4
	v_mov_b32_e32 v4, s27
	v_add_f32_e32 v8, 1.0, v7
	v_rcp_f32_e32 v8, v8
	s_nop 0
	v_mul_f32_e32 v7, v7, v8
	v_cndmask_b32_e32 v9, v7, v8, vcc
	v_cndmask_b32_e32 v7, v8, v7, vcc
	v_cmp_lt_i32_e32 vcc, v192, v83
	s_nop 1
	v_cndmask_b32_e32 v7, 1.0, v7, vcc
	v_mul_f32_e32 v8, v7, v5
	v_mul_f32_e32 v5, 0x3e0293ee, v95
	v_cndmask_b32_e32 v4, v4, v9, vcc
	v_exp_f32_e64 v9, -|v5|
	v_cmp_lt_f32_e32 vcc, 0, v5
	v_mov_b32_e32 v5, s27
	v_add_f32_e32 v10, 1.0, v9
	v_rcp_f32_e32 v10, v10
	s_nop 0
	v_mul_f32_e32 v9, v9, v10
	v_cndmask_b32_e32 v11, v9, v10, vcc
	v_cndmask_b32_e32 v9, v10, v9, vcc
	v_cmp_lt_i32_e32 vcc, v193, v83
	s_nop 1
	v_cndmask_b32_e32 v10, 1.0, v9, vcc
	v_cndmask_b32_e32 v5, v5, v11, vcc
	v_mul_f32_e32 v11, v10, v8
	ds_bpermute_b32 v12, v81, v11
	s_waitcnt lgkmcnt(0)
	v_cndmask_b32_e64 v8, 1.0, v12, s[36:37]
	v_mul_f32_e32 v9, v153, v8
	v_mul_f32_e32 v8, v10, v9
	v_mul_f32_e32 v10, v11, v12
	v_mul_f32_e32 v89, v153, v10
	v_mul_f32_e32 v10, 0x3e0293ee, v88
	v_exp_f32_e64 v11, -|v10|
	v_cmp_lt_f32_e32 vcc, 0, v10
	v_mov_b32_e32 v10, s27
	v_mul_f32_e32 v7, v7, v8
	v_add_f32_e32 v12, 1.0, v11
	v_rcp_f32_e32 v12, v12
	v_mul_f32_e32 v6, v6, v7
	v_pk_mul_f32 v[2:3], v[2:3], v[6:7]
	v_pk_mul_f32 v[4:5], v[4:5], v[8:9]
	v_mul_f32_e32 v11, v11, v12
	v_cndmask_b32_e32 v13, v11, v12, vcc
	v_cndmask_b32_e32 v11, v12, v11, vcc
	v_cmp_lt_i32_e32 vcc, v194, v83
	s_nop 1
	v_cndmask_b32_e32 v12, 1.0, v11, vcc
	v_exp_f32_e64 v11, -|v208|
	v_cndmask_b32_e32 v10, v10, v13, vcc
	v_cmp_lt_f32_e32 vcc, 0, v208
	v_add_f32_e32 v13, 1.0, v11
	v_rcp_f32_e32 v13, v13
	s_nop 0
	v_mul_f32_e32 v11, v11, v13
	v_cndmask_b32_e32 v14, v11, v13, vcc
	v_cndmask_b32_e32 v13, v13, v11, vcc
	v_cmp_lt_i32_e32 vcc, v195, v83
	v_mov_b32_e32 v11, s27
	s_nop 0
	v_cndmask_b32_e32 v11, v11, v14, vcc
	v_cndmask_b32_e32 v14, 1.0, v13, vcc
	v_mul_f32_e32 v13, v12, v14
	v_mul_f32_e32 v12, 0x3e0293ee, v90
	v_exp_f32_e64 v15, -|v12|
	v_cmp_lt_f32_e32 vcc, 0, v12
	v_mov_b32_e32 v12, s27
	v_add_f32_e32 v91, 1.0, v15
	v_rcp_f32_e32 v91, v91
	s_nop 0
	v_mul_f32_e32 v15, v15, v91
	v_cndmask_b32_e32 v154, v15, v91, vcc
	v_cndmask_b32_e32 v15, v91, v15, vcc
	v_cmp_lt_i32_e32 vcc, v196, v83
	s_nop 1
	v_cndmask_b32_e32 v15, 1.0, v15, vcc
	v_mul_f32_e32 v91, v15, v13
	v_exp_f32_e64 v13, -|v152|
	v_cndmask_b32_e32 v12, v12, v154, vcc
	v_cmp_lt_f32_e32 vcc, 0, v152
	v_add_f32_e32 v154, 1.0, v13
	v_rcp_f32_e32 v154, v154
	s_nop 0
	v_mul_f32_e32 v13, v13, v154
	v_cndmask_b32_e32 v155, v13, v154, vcc
	v_cndmask_b32_e32 v154, v154, v13, vcc
	v_cmp_lt_i32_e32 vcc, v197, v83
	v_mov_b32_e32 v13, s27
	s_nop 0
	v_cndmask_b32_e32 v154, 1.0, v154, vcc
	v_mul_f32_e32 v91, v154, v91
	ds_bpermute_b32 v156, v81, v91
	v_cndmask_b32_e32 v13, v13, v155, vcc
	s_waitcnt lgkmcnt(0)
	v_cndmask_b32_e64 v155, 1.0, v156, s[36:37]
	v_mul_f32_e32 v91, v91, v156
	v_mul_f32_e32 v155, v89, v155
	v_mul_f32_e32 v91, v91, v89
	v_mul_f32_e32 v89, 0x3e0293ee, v84
	v_exp_f32_e64 v156, -|v89|
	v_cmp_lt_f32_e32 vcc, 0, v89
	v_mul_f32_e32 v154, v154, v155
	v_mul_f32_e32 v15, v15, v154
	v_add_f32_e32 v157, 1.0, v156
	v_rcp_f32_e32 v157, v157
	v_mul_f32_e32 v14, v14, v15
	v_pk_mul_f32 v[12:13], v[12:13], v[154:155]
	v_pk_mul_f32 v[10:11], v[10:11], v[14:15]
	v_mul_f32_e32 v156, v156, v157
	v_cndmask_b32_e32 v89, v156, v157, vcc
	v_cndmask_b32_e32 v157, v157, v156, vcc
	v_cmp_lt_i32_e32 vcc, v198, v83
	v_mov_b32_e32 v156, s27
	s_nop 0
	v_cndmask_b32_e32 v156, v156, v89, vcc
	v_mul_f32_e32 v89, 0x3e0293ee, v85
	v_cndmask_b32_e32 v158, 1.0, v157, vcc
	v_exp_f32_e64 v157, -|v89|
	v_cmp_lt_f32_e32 vcc, 0, v89
	v_mov_b32_e32 v89, s27
	v_add_f32_e32 v159, 1.0, v157
	v_rcp_f32_e32 v159, v159
	s_nop 0
	v_mul_f32_e32 v157, v157, v159
	v_cndmask_b32_e32 v160, v157, v159, vcc
	v_cndmask_b32_e32 v159, v159, v157, vcc
	v_cmp_lt_i32_e32 vcc, v199, v83
	s_nop 1
	v_cndmask_b32_e32 v157, v89, v160, vcc
	v_cndmask_b32_e32 v160, 1.0, v159, vcc
	v_mul_f32_e32 v89, v158, v160
	v_mul_f32_e32 v158, 0x3e0293ee, v86
	v_exp_f32_e64 v159, -|v158|
	v_cmp_lt_f32_e32 vcc, 0, v158
	v_mov_b32_e32 v158, s27
	v_add_f32_e32 v161, 1.0, v159
	v_rcp_f32_e32 v161, v161
	s_nop 0
	v_mul_f32_e32 v159, v159, v161
	v_cndmask_b32_e32 v162, v159, v161, vcc
	v_cndmask_b32_e32 v159, v161, v159, vcc
	v_cmp_lt_i32_e32 vcc, v200, v83
	s_nop 1
	v_cndmask_b32_e32 v161, 1.0, v159, vcc
	v_cndmask_b32_e32 v158, v158, v162, vcc
	v_mul_f32_e32 v162, v161, v89
	v_mul_f32_e32 v89, 0x3e0293ee, v87
	v_exp_f32_e64 v159, -|v89|
	v_cmp_lt_f32_e32 vcc, 0, v89
	v_mov_b32_e32 v89, s27
	v_add_f32_e32 v163, 1.0, v159
	v_rcp_f32_e32 v163, v163
	s_nop 0
	v_mul_f32_e32 v159, v159, v163
	v_cndmask_b32_e32 v164, v159, v163, vcc
	v_cndmask_b32_e32 v163, v163, v159, vcc
	v_cmp_lt_i32_e32 vcc, v201, v83
	s_nop 1
	v_cndmask_b32_e32 v159, v89, v164, vcc
	v_cndmask_b32_e32 v89, 1.0, v163, vcc
	v_mul_f32_e32 v164, v89, v162
	ds_bpermute_b32 v165, v81, v164
	s_waitcnt lgkmcnt(0)
	v_cndmask_b32_e64 v162, 1.0, v165, s[36:37]
	v_mul_f32_e32 v163, v91, v162
	v_mul_f32_e32 v162, v89, v163
	v_mul_f32_e32 v89, v164, v165
	v_mul_f32_e32 v91, v89, v91
	v_mul_f32_e32 v89, 0x3e0293ee, v80
	v_exp_f32_e64 v164, -|v89|
	v_cmp_lt_f32_e32 vcc, 0, v89
	v_mul_f32_e32 v161, v161, v162
	v_mul_f32_e32 v160, v160, v161
	v_add_f32_e32 v165, 1.0, v164
	v_rcp_f32_e32 v165, v165
	v_pk_mul_f32 v[158:159], v[158:159], v[162:163]
	v_pk_mul_f32 v[156:157], v[156:157], v[160:161]
	v_mul_f32_e32 v164, v164, v165
	v_cndmask_b32_e32 v89, v164, v165, vcc
	v_cndmask_b32_e32 v165, v165, v164, vcc
	v_cmp_lt_i32_e32 vcc, v186, v83
	v_mov_b32_e32 v164, s27
	s_nop 0
	v_cndmask_b32_e32 v164, v164, v89, vcc
	v_exp_f32_e64 v89, -|v207|
	v_cndmask_b32_e32 v178, 1.0, v165, vcc
	v_cmp_lt_f32_e32 vcc, 0, v207
	v_add_f32_e32 v165, 1.0, v89
	v_rcp_f32_e32 v165, v165
	s_nop 0
	v_mul_f32_e32 v89, v89, v165
	v_cndmask_b32_e32 v179, v89, v165, vcc
	v_cndmask_b32_e32 v209, v165, v89, vcc
	v_cmp_lt_i32_e32 vcc, v202, v83
	v_mov_b32_e32 v89, s27
	s_nop 0
	v_cndmask_b32_e32 v165, v89, v179, vcc
	v_cndmask_b32_e32 v89, 1.0, v209, vcc
	v_mul_f32_e32 v179, v178, v89
	v_mul_f32_e32 v178, 0x3e0293ee, v82
	v_exp_f32_e64 v209, -|v178|
	v_cmp_lt_f32_e32 vcc, 0, v178
	v_mov_b32_e32 v178, s27
	v_add_f32_e32 v222, 1.0, v209
	v_rcp_f32_e32 v222, v222
	s_nop 0
	v_mul_f32_e32 v209, v209, v222
	v_cndmask_b32_e32 v223, v209, v222, vcc
	v_cndmask_b32_e32 v209, v222, v209, vcc
	v_cmp_lt_i32_e32 vcc, v203, v83
	s_nop 1
	v_cndmask_b32_e32 v209, 1.0, v209, vcc
	v_mul_f32_e32 v222, v209, v179
	v_exp_f32_e64 v179, -|v206|
	v_cndmask_b32_e32 v178, v178, v223, vcc
	v_cmp_lt_f32_e32 vcc, 0, v206
	v_add_f32_e32 v223, 1.0, v179
	v_rcp_f32_e32 v223, v223
	s_nop 0
	v_mul_f32_e32 v179, v179, v223
	v_cndmask_b32_e32 v224, v179, v223, vcc
	v_cndmask_b32_e32 v223, v223, v179, vcc
	v_cmp_lt_i32_e32 vcc, v204, v83
	v_mov_b32_e32 v83, s27
	s_nop 0
	v_cndmask_b32_e32 v179, v83, v224, vcc
	v_cndmask_b32_e32 v83, 1.0, v223, vcc
	v_mul_f32_e32 v226, v83, v222
	ds_bpermute_b32 v81, v81, v226
	s_waitcnt lgkmcnt(0)
	v_cndmask_b32_e64 v222, 1.0, v81, s[36:37]
	v_mul_f32_e32 v223, v91, v222
	v_mul_f32_e32 v222, v83, v223
	v_mul_f32_e32 v225, v209, v222
	v_mul_f32_e32 v224, v89, v225
	v_mul_f32_e32 v6, v226, v81
	v_pk_mul_f32 v[178:179], v[178:179], v[222:223]
	v_pk_mul_f32 v[164:165], v[164:165], v[224:225]
	v_mul_f32_e32 v6, v6, v91

.LBB0_552:
	v_add_u32_e32 v7, v205, v189
	v_cvt_pk_bf16_f32 v8, v10, v11
	v_cvt_pk_bf16_f32 v10, v2, v3
	v_cvt_pk_bf16_f32 v11, v4, v5
	ds_read_b64_tr_b16 v[222:223], v7 offset:34816
	ds_read_b64_tr_b16 v[224:225], v7 offset:37376
	ds_read_b64_tr_b16 v[226:227], v7 offset:39936
	ds_read_b64_tr_b16 v[228:229], v7 offset:42496
	ds_read_b64_tr_b16 v[230:231], v7 offset:34880
	ds_read_b64_tr_b16 v[232:233], v7 offset:37440
	ds_read_b64_tr_b16 v[234:235], v7 offset:40000
	ds_read_b64_tr_b16 v[236:237], v7 offset:42560
	ds_read_b64_tr_b16 v[238:239], v7 offset:34944
	ds_read_b64_tr_b16 v[240:241], v7 offset:37504
	ds_read_b64_tr_b16 v[242:243], v7 offset:40064
	ds_read_b64_tr_b16 v[244:245], v7 offset:42624
	v_cvt_pk_bf16_f32 v80, v164, v165
	v_cvt_pk_bf16_f32 v81, v178, v179
	v_cvt_pk_bf16_f32 v82, v156, v157
	v_cvt_pk_bf16_f32 v83, v158, v159
	v_cvt_pk_bf16_f32 v9, v12, v13
	v_mov_b32_e32 v153, v6
	s_waitcnt lgkmcnt(10)
	v_mfma_f32_32x32x16_bf16 v[16:31], v[222:225], v[80:83], v[16:31]
	ds_read_b64_tr_b16 v[84:85], v7 offset:35008
	ds_read_b64_tr_b16 v[86:87], v7 offset:37568
	s_waitcnt lgkmcnt(10)
	v_mfma_f32_32x32x16_bf16 v[16:31], v[226:229], v[8:11], v[16:31]
	ds_read_b64_tr_b16 v[88:89], v7 offset:40128
	ds_read_b64_tr_b16 v[90:91], v7 offset:42688
	s_waitcnt lgkmcnt(10)
	v_mfma_f32_32x32x16_bf16 v[32:47], v[230:233], v[80:83], v[32:47]
	s_waitcnt lgkmcnt(8)
	v_mfma_f32_32x32x16_bf16 v[32:47], v[234:237], v[8:11], v[32:47]
	s_waitcnt lgkmcnt(6)
	v_mfma_f32_32x32x16_bf16 v[48:63], v[238:241], v[80:83], v[48:63]
	s_waitcnt lgkmcnt(4)
	v_mfma_f32_32x32x16_bf16 v[48:63], v[242:245], v[8:11], v[48:63]
	s_waitcnt lgkmcnt(2)
	v_mfma_f32_32x32x16_bf16 v[64:79], v[84:87], v[80:83], v[64:79]
	s_waitcnt lgkmcnt(0)
	v_mfma_f32_32x32x16_bf16 v[64:79], v[88:91], v[8:11], v[64:79]

.LBB0_593:
	s_waitcnt vmcnt(2)
	v_ashrrev_i32_e32 v8, 4, v1
	v_ashrrev_i32_e32 v9, 31, v8
	v_lshlrev_b64 v[4:5], 13, v[8:9]
	v_lshl_add_u64 v[4:5], v[2:3], 0, v[4:5]
	s_mov_b32 s8, 0x40000
	s_mov_b32 s9, 0
	v_mad_u32_u24 v8, v8, s11, v178
	global_load_dwordx4 v[48:51], v[4:5], off
	v_lshl_add_u64 v[4:5], v[4:5], 0, s[8:9]
	global_load_dwordx4 v[52:55], v[4:5], off
	v_lshl_add_u64 v[4:5], v[4:5], 0, s[8:9]
	global_load_dwordx4 v[56:59], v[4:5], off
	v_lshl_add_u64 v[4:5], v[4:5], 0, s[8:9]
	global_load_dwordx4 v[60:63], v[4:5], off
	v_lshl_add_u64 v[4:5], v[4:5], 0, s[8:9]
	global_load_dwordx4 v[64:67], v[4:5], off
	v_lshl_add_u64 v[4:5], v[4:5], 0, s[8:9]
	global_load_dwordx4 v[68:71], v[4:5], off
	v_lshl_add_u64 v[4:5], v[4:5], 0, s[8:9]
	global_load_dwordx4 v[72:75], v[4:5], off
	v_lshl_add_u64 v[4:5], v[4:5], 0, s[8:9]
	global_load_dwordx4 v[76:79], v[4:5], off
	s_waitcnt vmcnt(7)
	ds_write_b128 v8, v[48:51]
	s_waitcnt vmcnt(6)
	ds_write_b128 v8, v[52:55] offset:8704
	s_waitcnt vmcnt(5)
	ds_write_b128 v8, v[56:59] offset:17408
	s_waitcnt vmcnt(4)
	ds_write_b128 v8, v[60:63] offset:26112
	s_waitcnt vmcnt(3)
	ds_write_b128 v8, v[64:67] offset:34816
	s_waitcnt vmcnt(2)
	ds_write_b128 v8, v[68:71] offset:43520
	s_waitcnt vmcnt(1)
	ds_write_b128 v8, v[72:75] offset:52224
	s_waitcnt vmcnt(0)
	ds_write_b128 v8, v[76:79] offset:60928
	s_movk_i32 s7, 0x1000
	s_lshl_b32 s5, s5, 1
	s_add_u32 s8, s82, s5
	s_addc_u32 s9, s90, 0
	s_lshr_b32 s6, s6, 1
	v_and_b32_e32 v10, 31, v1
	s_and_b32 s6, s6, 0xfffffe0
	v_or_b32_e32 v2, s6, v10
	v_bfe_u32 v179, v1, 5, 1
	v_mul_lo_u32 v2, v2, s11
	v_add_u32_e32 v183, 0, v2
	v_lshlrev_b32_e32 v222, 4, v179
	v_add_u32_e32 v2, v183, v222
	s_waitcnt lgkmcnt(0)
	s_barrier
	ds_read_b128 v[98:101], v2
	ds_read_b128 v[102:105], v2 offset:32
	ds_read_b128 v[106:109], v2 offset:64
	ds_read_b128 v[110:113], v2 offset:96
	ds_read_b128 v[114:117], v2 offset:128
	ds_read_b128 v[118:121], v2 offset:160
	ds_read_b128 v[122:125], v2 offset:192
	ds_read_b128 v[126:129], v2 offset:224
	v_bfe_u32 v2, v1, 2, 2
	v_lshl_or_b32 v11, v179, 2, v2
	v_ashrrev_i32_e32 v2, 4, v1
	v_ashrrev_i32_e32 v3, 31, v2
	v_lshlrev_b64 v[4:5], 13, v[2:3]
	v_lshl_or_b32 v6, v180, 1, v4
	v_mov_b32_e32 v7, v5
	v_lshl_add_u64 v[6:7], s[8:9], 0, v[6:7]
	s_mov_b64 s[6:7], 0x40000
	v_lshl_add_u64 v[8:9], v[6:7], 0, s[6:7]
	s_mov_b32 s6, 0x40000
	s_waitcnt lgkmcnt(0)
	s_barrier
	global_load_dwordx4 v[130:133], v[6:7], off
	global_load_dwordx4 v[134:137], v[6:7], off offset:1024
	v_add_co_u32_e32 v6, vcc, s6, v6
	s_movk_i32 s6, 0x140
	s_nop 0
	v_addc_co_u32_e32 v7, vcc, 0, v7, vcc
	global_load_dwordx4 v[138:141], v[6:7], off
	global_load_dwordx4 v[142:145], v[8:9], off offset:1024
	v_and_b32_e32 v6, 64, v217
	v_mul_lo_u32 v228, v2, s6
	s_and_b32 s6, s22, 3
	v_xor_b32_e32 v3, 32, v217
	v_add_u32_e32 v6, 64, v6
	s_lshl_b32 s6, s6, 8
	v_cmp_lt_i32_e32 vcc, v3, v6
	v_or3_b32 v4, v4, s6, v182
	v_readlane_b32 s6, v246, 1
	v_lshlrev_b32_e32 v12, 1, v1
	v_lshlrev_b32_e32 v13, 3, v1
	v_cndmask_b32_e32 v3, v217, v3, vcc
	v_readlane_b32 s7, v246, 2
	v_mov_b32_e32 v147, 0
	s_mov_b32 s8, 0
	v_mul_u32_u24_e32 v224, 0x140, v11
	v_and_b32_e32 v225, 32, v12
	v_and_b32_e32 v226, 24, v13
	v_lshlrev_b32_e32 v223, 2, v3
	v_mul_lo_u32 v227, v2, s11
	v_mul_u32_u24_e32 v229, 0x110, v10
	v_lshl_add_u64 v[184:185], s[6:7], 0, v[4:5]
	v_mov_b32_e32 v155, 0xf149f2ca
	s_mov_b64 s[6:7], 0
	v_mov_b32_e32 v2, 0
	v_mov_b32_e32 v3, v147
	v_mov_b32_e32 v4, v147
	v_mov_b32_e32 v5, v147
	v_mov_b32_e32 v6, v147
	v_mov_b32_e32 v7, v147
	v_mov_b32_e32 v8, v147
	v_mov_b32_e32 v9, v147
	v_mov_b32_e32 v10, v147
	v_mov_b32_e32 v11, v147
	v_mov_b32_e32 v12, v147
	v_mov_b32_e32 v13, v147
	v_mov_b32_e32 v14, v147
	v_mov_b32_e32 v15, v147
	v_mov_b32_e32 v16, v147
	v_mov_b32_e32 v17, v147
	v_mov_b32_e32 v50, 0
	v_mov_b32_e32 v51, v147
	v_mov_b32_e32 v52, v147
	v_mov_b32_e32 v53, v147
	v_mov_b32_e32 v54, v147
	v_mov_b32_e32 v55, v147
	v_mov_b32_e32 v56, v147
	v_mov_b32_e32 v57, v147
	v_mov_b32_e32 v58, v147
	v_mov_b32_e32 v59, v147
	v_mov_b32_e32 v60, v147
	v_mov_b32_e32 v61, v147
	v_mov_b32_e32 v62, v147
	v_mov_b32_e32 v63, v147
	v_mov_b32_e32 v64, v147
	v_mov_b32_e32 v65, v147
	v_mov_b32_e32 v66, 0
	v_mov_b32_e32 v67, v147
	v_mov_b32_e32 v68, v147
	v_mov_b32_e32 v69, v147
	v_mov_b32_e32 v70, v147
	v_mov_b32_e32 v71, v147
	v_mov_b32_e32 v72, v147
	v_mov_b32_e32 v73, v147
	v_mov_b32_e32 v74, v147
	v_mov_b32_e32 v75, v147
	v_mov_b32_e32 v76, v147
	v_mov_b32_e32 v77, v147
	v_mov_b32_e32 v78, v147
	v_mov_b32_e32 v79, v147
	v_mov_b32_e32 v80, v147
	v_mov_b32_e32 v81, v147
	v_mov_b32_e32 v18, 0
	v_mov_b32_e32 v19, v147
	v_mov_b32_e32 v20, v147
	v_mov_b32_e32 v21, v147
	v_mov_b32_e32 v22, v147
	v_mov_b32_e32 v23, v147
	v_mov_b32_e32 v24, v147
	v_mov_b32_e32 v25, v147
	v_mov_b32_e32 v26, v147
	v_mov_b32_e32 v27, v147
	v_mov_b32_e32 v28, v147
	v_mov_b32_e32 v29, v147
	v_mov_b32_e32 v30, v147
	v_mov_b32_e32 v31, v147
	v_mov_b32_e32 v32, v147
	v_mov_b32_e32 v33, v147
	s_branch .LBB0_596

.LBB0_736:
	global_atomic_add v4, v[170:171], v212, off sc0
	v_cvt_f32_u32_e32 v1, v3
	v_sub_u32_e32 v5, 0, v3
	v_rcp_iflag_f32_e32 v1, v1
	s_nop 0
	v_mul_f32_e32 v1, 0x4f7ffffe, v1
	v_cvt_u32_f32_e32 v1, v1
	v_mul_lo_u32 v5, v5, v1
	v_mul_hi_u32 v5, v1, v5
	v_add_u32_e32 v1, v1, v5
	s_waitcnt vmcnt(0)
	v_mul_hi_u32 v1, v4, v1
	v_mul_lo_u32 v5, v1, v3
	v_sub_u32_e32 v5, v4, v5
	v_add_u32_e32 v6, 1, v1
	v_cmp_ge_u32_e32 vcc, v5, v3
	v_add_u32_e32 v4, 1, v4
	s_nop 0
	v_cndmask_b32_e32 v1, v1, v6, vcc
	v_sub_u32_e32 v6, v5, v3
	v_cndmask_b32_e32 v5, v5, v6, vcc
	v_add_u32_e32 v6, 1, v1
	v_cmp_ge_u32_e32 vcc, v5, v3
	s_nop 1
	v_cndmask_b32_e32 v1, v1, v6, vcc
	v_mul_lo_u32 v5, v3, v1
	v_add_u32_e32 v3, v5, v3
	v_cmp_ne_u32_e32 vcc, v4, v3
	s_and_saveexec_b64 s[4:5], vcc
	s_xor_b64 s[6:7], exec, s[4:5]
	s_cbranch_execz .LBB0_750
	s_waitcnt lgkmcnt(0)
	v_mov_b32_e32 v2, 0x3300
	global_load_dword v2, v2, s[22:23] sc1
	s_waitcnt vmcnt(0)
	v_cmp_eq_u32_e32 vcc, v2, v1
	s_and_saveexec_b64 s[8:9], vcc
	s_cbranch_execz .LBB0_749
	s_mov_b32 s3, 1
	s_mov_b64 s[24:25], 0
	s_branch .LBB0_740

.LBB0_742:
	v_mov_b32_e32 v2, 0x3300
	global_load_dword v2, v2, s[22:23] sc1
	s_add_i32 s3, s3, 1
	s_mov_b64 s[40:41], -1
	s_waitcnt vmcnt(0)
	v_cmp_ne_u32_e32 vcc, v2, v1
	s_orn2_b64 s[38:39], vcc, exec
	s_branch .LBB0_739

.LBB0_788:
	s_mov_b32 s21, 0x4b800000
	v_readlane_b32 s92, v246, 13
	v_readlane_b32 s86, v246, 3
	v_readlane_b32 s93, v246, 14
	v_readlane_b32 s87, v246, 4
	s_mov_b64 s[12:13], 0xb0000
	s_waitcnt vmcnt(15)
	v_lshlrev_b32_e32 v144, 16, v152
	v_and_b32_e32 v145, 0xffff0000, v152
	v_lshlrev_b32_e32 v146, 16, v153
	v_and_b32_e32 v147, 0xffff0000, v153
	v_pk_add_f32 v[126:127], v[126:127], v[144:145]
	v_pk_add_f32 v[128:129], v[128:129], v[146:147]
	v_lshlrev_b32_e32 v144, 16, v154
	v_and_b32_e32 v145, 0xffff0000, v154
	v_lshlrev_b32_e32 v146, 16, v155
	v_and_b32_e32 v147, 0xffff0000, v155
	v_pk_add_f32 v[122:123], v[122:123], v[144:145]
	v_pk_add_f32 v[124:125], v[124:125], v[146:147]
	v_mul_f32_e32 v144, v127, v127
	v_mul_f32_e32 v145, v129, v129
	v_fmac_f32_e32 v144, v126, v126
	v_fmac_f32_e32 v145, v128, v128
	v_mul_f32_e32 v146, v123, v123
	v_mul_f32_e32 v147, v125, v125
	v_add_f32_e32 v144, v144, v145
	v_fmac_f32_e32 v146, v122, v122
	v_fmac_f32_e32 v147, v124, v124
	v_add_f32_e32 v146, v146, v147
	v_add_f32_e32 v151, v144, v146
	v_cvt_pk_bf16_f32 v126, v126, v127
	v_cvt_pk_bf16_f32 v127, v128, v129
	v_cvt_pk_bf16_f32 v128, v122, v123
	v_cvt_pk_bf16_f32 v129, v124, v125
	s_waitcnt vmcnt(14)
	v_lshlrev_b32_e32 v144, 16, v156
	v_and_b32_e32 v145, 0xffff0000, v156
	v_lshlrev_b32_e32 v146, 16, v157
	v_and_b32_e32 v147, 0xffff0000, v157
	v_pk_add_f32 v[118:119], v[118:119], v[144:145]
	v_pk_add_f32 v[120:121], v[120:121], v[146:147]
	v_lshlrev_b32_e32 v144, 16, v158
	v_and_b32_e32 v145, 0xffff0000, v158
	v_lshlrev_b32_e32 v146, 16, v159
	v_and_b32_e32 v147, 0xffff0000, v159
	v_pk_add_f32 v[114:115], v[114:115], v[144:145]
	v_pk_add_f32 v[116:117], v[116:117], v[146:147]
	v_mul_f32_e32 v144, v119, v119
	v_mul_f32_e32 v145, v121, v121
	v_fmac_f32_e32 v144, v118, v118
	v_fmac_f32_e32 v145, v120, v120
	v_mul_f32_e32 v146, v115, v115
	v_mul_f32_e32 v147, v117, v117
	v_add_f32_e32 v144, v144, v145
	v_fmac_f32_e32 v146, v114, v114
	v_fmac_f32_e32 v147, v116, v116
	v_add_f32_e32 v146, v146, v147
	v_add_f32_e32 v144, v144, v146
	v_add_f32_e32 v122, v151, v144
	v_cvt_pk_bf16_f32 v118, v118, v119
	v_cvt_pk_bf16_f32 v119, v120, v121
	v_cvt_pk_bf16_f32 v120, v114, v115
	v_cvt_pk_bf16_f32 v121, v116, v117
	global_store_dwordx4 v142, v[126:129], s[14:15] sc1
	global_store_dwordx4 v142, v[118:121], s[14:15] offset:256 sc1
	s_waitcnt vmcnt(15)
	v_lshlrev_b32_e32 v144, 16, v160
	v_and_b32_e32 v145, 0xffff0000, v160
	v_lshlrev_b32_e32 v146, 16, v161
	v_and_b32_e32 v147, 0xffff0000, v161
	v_pk_add_f32 v[110:111], v[110:111], v[144:145]
	v_pk_add_f32 v[112:113], v[112:113], v[146:147]
	v_lshlrev_b32_e32 v144, 16, v162
	v_and_b32_e32 v145, 0xffff0000, v162
	v_lshlrev_b32_e32 v146, 16, v163
	v_and_b32_e32 v147, 0xffff0000, v163
	v_pk_add_f32 v[106:107], v[106:107], v[144:145]
	v_pk_add_f32 v[108:109], v[108:109], v[146:147]
	v_mul_f32_e32 v144, v111, v111
	v_mul_f32_e32 v145, v113, v113
	v_fmac_f32_e32 v144, v110, v110
	v_fmac_f32_e32 v145, v112, v112
	v_mul_f32_e32 v146, v107, v107
	v_mul_f32_e32 v147, v109, v109
	v_add_f32_e32 v144, v144, v145
	v_fmac_f32_e32 v146, v106, v106
	v_fmac_f32_e32 v147, v108, v108
	v_add_f32_e32 v146, v146, v147
	v_add_f32_e32 v151, v144, v146
	v_cvt_pk_bf16_f32 v110, v110, v111
	v_cvt_pk_bf16_f32 v111, v112, v113
	v_cvt_pk_bf16_f32 v112, v106, v107
	v_cvt_pk_bf16_f32 v113, v108, v109
	s_waitcnt vmcnt(14)
	v_lshlrev_b32_e32 v144, 16, v182
	v_and_b32_e32 v145, 0xffff0000, v182
	v_lshlrev_b32_e32 v146, 16, v183
	v_and_b32_e32 v147, 0xffff0000, v183
	v_pk_add_f32 v[102:103], v[102:103], v[144:145]
	v_pk_add_f32 v[104:105], v[104:105], v[146:147]
	v_lshlrev_b32_e32 v144, 16, v184
	v_and_b32_e32 v145, 0xffff0000, v184
	v_lshlrev_b32_e32 v146, 16, v185
	v_and_b32_e32 v147, 0xffff0000, v185
	v_pk_add_f32 v[98:99], v[98:99], v[144:145]
	v_pk_add_f32 v[100:101], v[100:101], v[146:147]
	v_mul_f32_e32 v144, v103, v103
	v_mul_f32_e32 v145, v105, v105
	v_fmac_f32_e32 v144, v102, v102
	v_fmac_f32_e32 v145, v104, v104
	v_mul_f32_e32 v146, v99, v99
	v_mul_f32_e32 v147, v101, v101
	v_add_f32_e32 v144, v144, v145
	v_fmac_f32_e32 v146, v98, v98
	v_fmac_f32_e32 v147, v100, v100
	v_add_f32_e32 v146, v146, v147
	v_add_f32_e32 v144, v144, v146
	v_add_f32_e32 v106, v151, v144
	v_cvt_pk_bf16_f32 v102, v102, v103
	v_cvt_pk_bf16_f32 v103, v104, v105
	v_cvt_pk_bf16_f32 v104, v98, v99
	v_cvt_pk_bf16_f32 v105, v100, v101
	v_add_u32_e32 v143, 0x10000, v142
	global_store_dwordx4 v143, v[110:113], s[14:15] sc1
	global_store_dwordx4 v143, v[102:105], s[14:15] offset:256 sc1
	s_waitcnt vmcnt(15)
	v_lshlrev_b32_e32 v144, 16, v186
	v_and_b32_e32 v145, 0xffff0000, v186
	v_lshlrev_b32_e32 v146, 16, v187
	v_and_b32_e32 v147, 0xffff0000, v187
	v_pk_add_f32 v[94:95], v[94:95], v[144:145]
	v_pk_add_f32 v[96:97], v[96:97], v[146:147]
	v_lshlrev_b32_e32 v144, 16, v188
	v_and_b32_e32 v145, 0xffff0000, v188
	v_lshlrev_b32_e32 v146, 16, v189
	v_and_b32_e32 v147, 0xffff0000, v189
	v_pk_add_f32 v[90:91], v[90:91], v[144:145]
	v_pk_add_f32 v[92:93], v[92:93], v[146:147]
	v_mul_f32_e32 v144, v95, v95
	v_mul_f32_e32 v145, v97, v97
	v_fmac_f32_e32 v144, v94, v94
	v_fmac_f32_e32 v145, v96, v96
	v_mul_f32_e32 v146, v91, v91
	v_mul_f32_e32 v147, v93, v93
	v_add_f32_e32 v144, v144, v145
	v_fmac_f32_e32 v146, v90, v90
	v_fmac_f32_e32 v147, v92, v92
	v_add_f32_e32 v146, v146, v147
	v_add_f32_e32 v151, v144, v146
	v_cvt_pk_bf16_f32 v94, v94, v95
	v_cvt_pk_bf16_f32 v95, v96, v97
	v_cvt_pk_bf16_f32 v96, v90, v91
	v_cvt_pk_bf16_f32 v97, v92, v93
	s_waitcnt vmcnt(14)
	v_lshlrev_b32_e32 v144, 16, v190
	v_and_b32_e32 v145, 0xffff0000, v190
	v_lshlrev_b32_e32 v146, 16, v191
	v_and_b32_e32 v147, 0xffff0000, v191
	v_pk_add_f32 v[86:87], v[86:87], v[144:145]
	v_pk_add_f32 v[88:89], v[88:89], v[146:147]
	v_lshlrev_b32_e32 v144, 16, v192
	v_and_b32_e32 v145, 0xffff0000, v192
	v_lshlrev_b32_e32 v146, 16, v193
	v_and_b32_e32 v147, 0xffff0000, v193
	v_pk_add_f32 v[82:83], v[82:83], v[144:145]
	v_pk_add_f32 v[84:85], v[84:85], v[146:147]
	v_mul_f32_e32 v144, v87, v87
	v_mul_f32_e32 v145, v89, v89
	v_fmac_f32_e32 v144, v86, v86
	v_fmac_f32_e32 v145, v88, v88
	v_mul_f32_e32 v146, v83, v83
	v_mul_f32_e32 v147, v85, v85
	v_add_f32_e32 v144, v144, v145
	v_fmac_f32_e32 v146, v82, v82
	v_fmac_f32_e32 v147, v84, v84
	v_add_f32_e32 v146, v146, v147
	v_add_f32_e32 v144, v144, v146
	v_add_f32_e32 v90, v151, v144
	v_cvt_pk_bf16_f32 v86, v86, v87
	v_cvt_pk_bf16_f32 v87, v88, v89
	v_cvt_pk_bf16_f32 v88, v82, v83
	v_cvt_pk_bf16_f32 v89, v84, v85
	v_add_u32_e32 v143, 0x20000, v142
	global_store_dwordx4 v143, v[94:97], s[14:15] sc1
	global_store_dwordx4 v143, v[86:89], s[14:15] offset:256 sc1
	s_waitcnt vmcnt(15)
	v_lshlrev_b32_e32 v144, 16, v194
	v_and_b32_e32 v145, 0xffff0000, v194
	v_lshlrev_b32_e32 v146, 16, v195
	v_and_b32_e32 v147, 0xffff0000, v195
	v_pk_add_f32 v[78:79], v[78:79], v[144:145]
	v_pk_add_f32 v[80:81], v[80:81], v[146:147]
	v_lshlrev_b32_e32 v144, 16, v196
	v_and_b32_e32 v145, 0xffff0000, v196
	v_lshlrev_b32_e32 v146, 16, v197
	v_and_b32_e32 v147, 0xffff0000, v197
	v_pk_add_f32 v[74:75], v[74:75], v[144:145]
	v_pk_add_f32 v[76:77], v[76:77], v[146:147]
	v_mul_f32_e32 v144, v79, v79
	v_mul_f32_e32 v145, v81, v81
	v_fmac_f32_e32 v144, v78, v78
	v_fmac_f32_e32 v145, v80, v80
	v_mul_f32_e32 v146, v75, v75
	v_mul_f32_e32 v147, v77, v77
	v_add_f32_e32 v144, v144, v145
	v_fmac_f32_e32 v146, v74, v74
	v_fmac_f32_e32 v147, v76, v76
	v_add_f32_e32 v146, v146, v147
	v_add_f32_e32 v151, v144, v146
	v_cvt_pk_bf16_f32 v78, v78, v79
	v_cvt_pk_bf16_f32 v79, v80, v81
	v_cvt_pk_bf16_f32 v80, v74, v75
	v_cvt_pk_bf16_f32 v81, v76, v77
	s_waitcnt vmcnt(14)
	v_lshlrev_b32_e32 v144, 16, v198
	v_and_b32_e32 v145, 0xffff0000, v198
	v_lshlrev_b32_e32 v146, 16, v199
	v_and_b32_e32 v147, 0xffff0000, v199
	v_pk_add_f32 v[70:71], v[70:71], v[144:145]
	v_pk_add_f32 v[72:73], v[72:73], v[146:147]
	v_lshlrev_b32_e32 v144, 16, v200
	v_and_b32_e32 v145, 0xffff0000, v200
	v_lshlrev_b32_e32 v146, 16, v201
	v_and_b32_e32 v147, 0xffff0000, v201
	v_pk_add_f32 v[66:67], v[66:67], v[144:145]
	v_pk_add_f32 v[68:69], v[68:69], v[146:147]
	v_mul_f32_e32 v144, v71, v71
	v_mul_f32_e32 v145, v73, v73
	v_fmac_f32_e32 v144, v70, v70
	v_fmac_f32_e32 v145, v72, v72
	v_mul_f32_e32 v146, v67, v67
	v_mul_f32_e32 v147, v69, v69
	v_add_f32_e32 v144, v144, v145
	v_fmac_f32_e32 v146, v66, v66
	v_fmac_f32_e32 v147, v68, v68
	v_add_f32_e32 v146, v146, v147
	v_add_f32_e32 v144, v144, v146
	v_add_f32_e32 v74, v151, v144
	v_cvt_pk_bf16_f32 v70, v70, v71
	v_cvt_pk_bf16_f32 v71, v72, v73
	v_cvt_pk_bf16_f32 v72, v66, v67
	v_cvt_pk_bf16_f32 v73, v68, v69
	v_add_u32_e32 v143, 0x30000, v142
	global_store_dwordx4 v143, v[78:81], s[14:15] sc1
	global_store_dwordx4 v143, v[70:73], s[14:15] offset:256 sc1
	s_waitcnt vmcnt(15)
	v_lshlrev_b32_e32 v144, 16, v202
	v_and_b32_e32 v145, 0xffff0000, v202
	v_lshlrev_b32_e32 v146, 16, v203
	v_and_b32_e32 v147, 0xffff0000, v203
	v_pk_add_f32 v[62:63], v[62:63], v[144:145]
	v_pk_add_f32 v[64:65], v[64:65], v[146:147]
	v_lshlrev_b32_e32 v144, 16, v204
	v_and_b32_e32 v145, 0xffff0000, v204
	v_lshlrev_b32_e32 v146, 16, v205
	v_and_b32_e32 v147, 0xffff0000, v205
	v_pk_add_f32 v[58:59], v[58:59], v[144:145]
	v_pk_add_f32 v[60:61], v[60:61], v[146:147]
	v_mul_f32_e32 v144, v63, v63
	v_mul_f32_e32 v145, v65, v65
	v_fmac_f32_e32 v144, v62, v62
	v_fmac_f32_e32 v145, v64, v64
	v_mul_f32_e32 v146, v59, v59
	v_mul_f32_e32 v147, v61, v61
	v_add_f32_e32 v144, v144, v145
	v_fmac_f32_e32 v146, v58, v58
	v_fmac_f32_e32 v147, v60, v60
	v_add_f32_e32 v146, v146, v147
	v_add_f32_e32 v151, v144, v146
	v_cvt_pk_bf16_f32 v62, v62, v63
	v_cvt_pk_bf16_f32 v63, v64, v65
	v_cvt_pk_bf16_f32 v64, v58, v59
	v_cvt_pk_bf16_f32 v65, v60, v61
	s_waitcnt vmcnt(14)
	v_lshlrev_b32_e32 v144, 16, v206
	v_and_b32_e32 v145, 0xffff0000, v206
	v_lshlrev_b32_e32 v146, 16, v207
	v_and_b32_e32 v147, 0xffff0000, v207
	v_pk_add_f32 v[54:55], v[54:55], v[144:145]
	v_pk_add_f32 v[56:57], v[56:57], v[146:147]
	v_lshlrev_b32_e32 v144, 16, v208
	v_and_b32_e32 v145, 0xffff0000, v208
	v_lshlrev_b32_e32 v146, 16, v209
	v_and_b32_e32 v147, 0xffff0000, v209
	v_pk_add_f32 v[50:51], v[50:51], v[144:145]
	v_pk_add_f32 v[52:53], v[52:53], v[146:147]
	v_mul_f32_e32 v144, v55, v55
	v_mul_f32_e32 v145, v57, v57
	v_fmac_f32_e32 v144, v54, v54
	v_fmac_f32_e32 v145, v56, v56
	v_mul_f32_e32 v146, v51, v51
	v_mul_f32_e32 v147, v53, v53
	v_add_f32_e32 v144, v144, v145
	v_fmac_f32_e32 v146, v50, v50
	v_fmac_f32_e32 v147, v52, v52
	v_add_f32_e32 v146, v146, v147
	v_add_f32_e32 v144, v144, v146
	v_add_f32_e32 v58, v151, v144
	v_cvt_pk_bf16_f32 v54, v54, v55
	v_cvt_pk_bf16_f32 v55, v56, v57
	v_cvt_pk_bf16_f32 v56, v50, v51
	v_cvt_pk_bf16_f32 v57, v52, v53
	v_add_u32_e32 v143, 0x80000, v142
	global_store_dwordx4 v143, v[62:65], s[14:15] sc1
	global_store_dwordx4 v143, v[54:57], s[14:15] offset:256 sc1
	s_waitcnt vmcnt(15)
	v_lshlrev_b32_e32 v144, 16, v222
	v_and_b32_e32 v145, 0xffff0000, v222
	v_lshlrev_b32_e32 v146, 16, v223
	v_and_b32_e32 v147, 0xffff0000, v223
	v_pk_add_f32 v[46:47], v[46:47], v[144:145]
	v_pk_add_f32 v[48:49], v[48:49], v[146:147]
	v_lshlrev_b32_e32 v144, 16, v224
	v_and_b32_e32 v145, 0xffff0000, v224
	v_lshlrev_b32_e32 v146, 16, v225
	v_and_b32_e32 v147, 0xffff0000, v225
	v_pk_add_f32 v[42:43], v[42:43], v[144:145]
	v_pk_add_f32 v[44:45], v[44:45], v[146:147]
	v_mul_f32_e32 v144, v47, v47
	v_mul_f32_e32 v145, v49, v49
	v_fmac_f32_e32 v144, v46, v46
	v_fmac_f32_e32 v145, v48, v48
	v_mul_f32_e32 v146, v43, v43
	v_mul_f32_e32 v147, v45, v45
	v_add_f32_e32 v144, v144, v145
	v_fmac_f32_e32 v146, v42, v42
	v_fmac_f32_e32 v147, v44, v44
	v_add_f32_e32 v146, v146, v147
	v_add_f32_e32 v151, v144, v146
	v_cvt_pk_bf16_f32 v46, v46, v47
	v_cvt_pk_bf16_f32 v47, v48, v49
	v_cvt_pk_bf16_f32 v48, v42, v43
	v_cvt_pk_bf16_f32 v49, v44, v45
	s_waitcnt vmcnt(14)
	v_lshlrev_b32_e32 v144, 16, v226
	v_and_b32_e32 v145, 0xffff0000, v226
	v_lshlrev_b32_e32 v146, 16, v227
	v_and_b32_e32 v147, 0xffff0000, v227
	v_pk_add_f32 v[38:39], v[38:39], v[144:145]
	v_pk_add_f32 v[40:41], v[40:41], v[146:147]
	v_lshlrev_b32_e32 v144, 16, v228
	v_and_b32_e32 v145, 0xffff0000, v228
	v_lshlrev_b32_e32 v146, 16, v229
	v_and_b32_e32 v147, 0xffff0000, v229
	v_pk_add_f32 v[34:35], v[34:35], v[144:145]
	v_pk_add_f32 v[36:37], v[36:37], v[146:147]
	v_mul_f32_e32 v144, v39, v39
	v_mul_f32_e32 v145, v41, v41
	v_fmac_f32_e32 v144, v38, v38
	v_fmac_f32_e32 v145, v40, v40
	v_mul_f32_e32 v146, v35, v35
	v_mul_f32_e32 v147, v37, v37
	v_add_f32_e32 v144, v144, v145
	v_fmac_f32_e32 v146, v34, v34
	v_fmac_f32_e32 v147, v36, v36
	v_add_f32_e32 v146, v146, v147
	v_add_f32_e32 v144, v144, v146
	v_add_f32_e32 v42, v151, v144
	v_cvt_pk_bf16_f32 v38, v38, v39
	v_cvt_pk_bf16_f32 v39, v40, v41
	v_cvt_pk_bf16_f32 v40, v34, v35
	v_cvt_pk_bf16_f32 v41, v36, v37
	v_add_u32_e32 v143, 0x90000, v142
	global_store_dwordx4 v143, v[46:49], s[14:15] sc1
	global_store_dwordx4 v143, v[38:41], s[14:15] offset:256 sc1
	s_waitcnt vmcnt(15)
	v_lshlrev_b32_e32 v144, 16, v230
	v_and_b32_e32 v145, 0xffff0000, v230
	v_lshlrev_b32_e32 v146, 16, v231
	v_and_b32_e32 v147, 0xffff0000, v231
	v_pk_add_f32 v[30:31], v[30:31], v[144:145]
	v_pk_add_f32 v[32:33], v[32:33], v[146:147]
	v_lshlrev_b32_e32 v144, 16, v232
	v_and_b32_e32 v145, 0xffff0000, v232
	v_lshlrev_b32_e32 v146, 16, v233
	v_and_b32_e32 v147, 0xffff0000, v233
	v_pk_add_f32 v[26:27], v[26:27], v[144:145]
	v_pk_add_f32 v[28:29], v[28:29], v[146:147]
	v_mul_f32_e32 v144, v31, v31
	v_mul_f32_e32 v145, v33, v33
	v_fmac_f32_e32 v144, v30, v30
	v_fmac_f32_e32 v145, v32, v32
	v_mul_f32_e32 v146, v27, v27
	v_mul_f32_e32 v147, v29, v29
	v_add_f32_e32 v144, v144, v145
	v_fmac_f32_e32 v146, v26, v26
	v_fmac_f32_e32 v147, v28, v28
	v_add_f32_e32 v146, v146, v147
	v_add_f32_e32 v151, v144, v146
	v_cvt_pk_bf16_f32 v30, v30, v31
	v_cvt_pk_bf16_f32 v31, v32, v33
	v_cvt_pk_bf16_f32 v32, v26, v27
	v_cvt_pk_bf16_f32 v33, v28, v29
	s_waitcnt vmcnt(14)
	v_lshlrev_b32_e32 v144, 16, v234
	v_and_b32_e32 v145, 0xffff0000, v234
	v_lshlrev_b32_e32 v146, 16, v235
	v_and_b32_e32 v147, 0xffff0000, v235
	v_pk_add_f32 v[22:23], v[22:23], v[144:145]
	v_pk_add_f32 v[24:25], v[24:25], v[146:147]
	v_lshlrev_b32_e32 v144, 16, v236
	v_and_b32_e32 v145, 0xffff0000, v236
	v_lshlrev_b32_e32 v146, 16, v237
	v_and_b32_e32 v147, 0xffff0000, v237
	v_pk_add_f32 v[18:19], v[18:19], v[144:145]
	v_pk_add_f32 v[20:21], v[20:21], v[146:147]
	v_mul_f32_e32 v144, v23, v23
	v_mul_f32_e32 v145, v25, v25
	v_fmac_f32_e32 v144, v22, v22
	v_fmac_f32_e32 v145, v24, v24
	v_mul_f32_e32 v146, v19, v19
	v_mul_f32_e32 v147, v21, v21
	v_add_f32_e32 v144, v144, v145
	v_fmac_f32_e32 v146, v18, v18
	v_fmac_f32_e32 v147, v20, v20
	v_add_f32_e32 v146, v146, v147
	v_add_f32_e32 v144, v144, v146
	v_add_f32_e32 v26, v151, v144
	v_cvt_pk_bf16_f32 v22, v22, v23
	v_cvt_pk_bf16_f32 v23, v24, v25
	v_cvt_pk_bf16_f32 v24, v18, v19
	v_cvt_pk_bf16_f32 v25, v20, v21
	v_add_u32_e32 v143, 0xa0000, v142
	global_store_dwordx4 v143, v[30:33], s[14:15] sc1
	global_store_dwordx4 v143, v[22:25], s[14:15] offset:256 sc1
	s_waitcnt vmcnt(15)
	v_lshlrev_b32_e32 v144, 16, v238
	v_and_b32_e32 v145, 0xffff0000, v238
	v_lshlrev_b32_e32 v146, 16, v239
	v_and_b32_e32 v147, 0xffff0000, v239
	v_pk_add_f32 v[14:15], v[14:15], v[144:145]
	v_pk_add_f32 v[16:17], v[16:17], v[146:147]
	v_lshlrev_b32_e32 v144, 16, v240
	v_and_b32_e32 v145, 0xffff0000, v240
	v_lshlrev_b32_e32 v146, 16, v241
	v_and_b32_e32 v147, 0xffff0000, v241
	v_pk_add_f32 v[10:11], v[10:11], v[144:145]
	v_pk_add_f32 v[12:13], v[12:13], v[146:147]
	v_mul_f32_e32 v144, v15, v15
	v_mul_f32_e32 v145, v17, v17
	v_fmac_f32_e32 v144, v14, v14
	v_fmac_f32_e32 v145, v16, v16
	v_mul_f32_e32 v146, v11, v11
	v_mul_f32_e32 v147, v13, v13
	v_add_f32_e32 v144, v144, v145
	v_fmac_f32_e32 v146, v10, v10
	v_fmac_f32_e32 v147, v12, v12
	v_add_f32_e32 v146, v146, v147
	v_add_f32_e32 v151, v144, v146
	v_cvt_pk_bf16_f32 v14, v14, v15
	v_cvt_pk_bf16_f32 v15, v16, v17
	v_cvt_pk_bf16_f32 v16, v10, v11
	v_cvt_pk_bf16_f32 v17, v12, v13
	s_waitcnt vmcnt(14)
	v_lshlrev_b32_e32 v144, 16, v242
	v_and_b32_e32 v145, 0xffff0000, v242
	v_lshlrev_b32_e32 v146, 16, v243
	v_and_b32_e32 v147, 0xffff0000, v243
	v_pk_add_f32 v[6:7], v[6:7], v[144:145]
	v_pk_add_f32 v[8:9], v[8:9], v[146:147]
	v_lshlrev_b32_e32 v144, 16, v244
	v_and_b32_e32 v145, 0xffff0000, v244
	v_lshlrev_b32_e32 v146, 16, v245
	v_and_b32_e32 v147, 0xffff0000, v245
	v_pk_add_f32 v[2:3], v[2:3], v[144:145]
	v_pk_add_f32 v[4:5], v[4:5], v[146:147]
	v_mul_f32_e32 v144, v7, v7
	v_mul_f32_e32 v145, v9, v9
	v_fmac_f32_e32 v144, v6, v6
	v_fmac_f32_e32 v145, v8, v8
	v_mul_f32_e32 v146, v3, v3
	v_mul_f32_e32 v147, v5, v5
	v_add_f32_e32 v144, v144, v145
	v_fmac_f32_e32 v146, v2, v2
	v_fmac_f32_e32 v147, v4, v4
	v_add_f32_e32 v146, v146, v147
	v_add_f32_e32 v144, v144, v146
	v_add_f32_e32 v10, v151, v144
	v_cvt_pk_bf16_f32 v6, v6, v7
	v_cvt_pk_bf16_f32 v7, v8, v9
	v_cvt_pk_bf16_f32 v8, v2, v3
	v_cvt_pk_bf16_f32 v9, v4, v5
	v_add_u32_e32 v143, 0xb0000, v142
	global_store_dwordx4 v143, v[14:17], s[14:15] sc1
	global_store_dwordx4 v143, v[6:9], s[14:15] offset:256 sc1
	v_and_b32_e32 v115, 64, v217
	v_xor_b32_e32 v114, 16, v217
	v_add_u32_e32 v115, 64, v115
	v_cmp_lt_i32_e32 vcc, v114, v115
	s_nop 1
	v_cndmask_b32_e32 v114, v217, v114, vcc
	v_lshlrev_b32_e32 v116, 2, v114
	v_xor_b32_e32 v114, 32, v217
	v_cmp_lt_i32_e32 vcc, v114, v115
	s_nop 1
	v_cndmask_b32_e32 v114, v217, v114, vcc
	v_lshlrev_b32_e32 v117, 2, v114
	ds_bpermute_b32 v123, v116, v122
	ds_bpermute_b32 v107, v116, v106
	ds_bpermute_b32 v91, v116, v90
	ds_bpermute_b32 v75, v116, v74
	ds_bpermute_b32 v59, v116, v58
	ds_bpermute_b32 v43, v116, v42
	ds_bpermute_b32 v27, v116, v26
	ds_bpermute_b32 v11, v116, v10
	s_waitcnt lgkmcnt(7)
	v_add_f32_e32 v122, v122, v123
	s_waitcnt lgkmcnt(6)
	v_add_f32_e32 v106, v106, v107
	s_waitcnt lgkmcnt(5)
	v_add_f32_e32 v90, v90, v91
	s_waitcnt lgkmcnt(4)
	v_add_f32_e32 v74, v74, v75
	s_waitcnt lgkmcnt(3)
	v_add_f32_e32 v58, v58, v59
	s_waitcnt lgkmcnt(2)
	v_add_f32_e32 v42, v42, v43
	s_waitcnt lgkmcnt(1)
	v_add_f32_e32 v26, v26, v27
	s_waitcnt lgkmcnt(0)
	v_add_f32_e32 v10, v10, v11
	ds_bpermute_b32 v123, v117, v122
	ds_bpermute_b32 v107, v117, v106
	ds_bpermute_b32 v91, v117, v90
	ds_bpermute_b32 v75, v117, v74
	ds_bpermute_b32 v59, v117, v58
	ds_bpermute_b32 v43, v117, v42
	ds_bpermute_b32 v27, v117, v26
	ds_bpermute_b32 v11, v117, v10
	s_and_saveexec_b64 s[50:51], s[36:37]
	s_waitcnt lgkmcnt(7)
	v_add_f32_e32 v122, v122, v123
	v_fma_f32 v122, v122, s21, 0.5
	v_trunc_f32_e32 v122, v122
	v_mul_f32_e32 v123, 0x2f800000, v122
	v_floor_f32_e32 v123, v123
	v_fmac_f32_e32 v122, 0xcf800000, v123
	v_cvt_u32_f32_e32 v122, v122
	v_cvt_u32_f32_e32 v123, v123
	global_atomic_add_x2 v180, v[122:123], s[24:25]
	s_waitcnt lgkmcnt(6)
	v_add_f32_e32 v106, v106, v107
	v_fma_f32 v106, v106, s21, 0.5
	v_trunc_f32_e32 v106, v106
	v_mul_f32_e32 v107, 0x2f800000, v106
	v_floor_f32_e32 v107, v107
	v_fmac_f32_e32 v106, 0xcf800000, v107
	v_cvt_u32_f32_e32 v106, v106
	v_cvt_u32_f32_e32 v107, v107
	global_atomic_add_x2 v180, v[106:107], s[24:25] offset:128
	s_waitcnt lgkmcnt(5)
	v_add_f32_e32 v90, v90, v91
	v_fma_f32 v90, v90, s21, 0.5
	v_trunc_f32_e32 v90, v90
	v_mul_f32_e32 v91, 0x2f800000, v90
	v_floor_f32_e32 v91, v91
	v_fmac_f32_e32 v90, 0xcf800000, v91
	v_cvt_u32_f32_e32 v90, v90
	v_cvt_u32_f32_e32 v91, v91
	global_atomic_add_x2 v180, v[90:91], s[24:25] offset:256
	s_waitcnt lgkmcnt(4)
	v_add_f32_e32 v74, v74, v75
	v_fma_f32 v74, v74, s21, 0.5
	v_trunc_f32_e32 v74, v74
	v_mul_f32_e32 v75, 0x2f800000, v74
	v_floor_f32_e32 v75, v75
	v_fmac_f32_e32 v74, 0xcf800000, v75
	v_cvt_u32_f32_e32 v74, v74
	v_cvt_u32_f32_e32 v75, v75
	global_atomic_add_x2 v180, v[74:75], s[24:25] offset:384
	s_waitcnt lgkmcnt(3)
	v_add_f32_e32 v58, v58, v59
	v_fma_f32 v58, v58, s21, 0.5
	v_trunc_f32_e32 v58, v58
	v_mul_f32_e32 v59, 0x2f800000, v58
	v_floor_f32_e32 v59, v59
	v_fmac_f32_e32 v58, 0xcf800000, v59
	v_cvt_u32_f32_e32 v58, v58
	v_cvt_u32_f32_e32 v59, v59
	global_atomic_add_x2 v180, v[58:59], s[24:25] offset:1024
	s_waitcnt lgkmcnt(2)
	v_add_f32_e32 v42, v42, v43
	v_fma_f32 v42, v42, s21, 0.5
	v_trunc_f32_e32 v42, v42
	v_mul_f32_e32 v43, 0x2f800000, v42
	v_floor_f32_e32 v43, v43
	v_fmac_f32_e32 v42, 0xcf800000, v43
	v_cvt_u32_f32_e32 v42, v42
	v_cvt_u32_f32_e32 v43, v43
	global_atomic_add_x2 v180, v[42:43], s[24:25] offset:1152
	s_waitcnt lgkmcnt(1)
	v_add_f32_e32 v26, v26, v27
	v_fma_f32 v26, v26, s21, 0.5
	v_trunc_f32_e32 v26, v26
	v_mul_f32_e32 v27, 0x2f800000, v26
	v_floor_f32_e32 v27, v27
	v_fmac_f32_e32 v26, 0xcf800000, v27
	v_cvt_u32_f32_e32 v26, v26
	v_cvt_u32_f32_e32 v27, v27
	global_atomic_add_x2 v180, v[26:27], s[24:25] offset:1280
	s_waitcnt lgkmcnt(0)
	v_add_f32_e32 v10, v10, v11
	v_fma_f32 v10, v10, s21, 0.5
	v_trunc_f32_e32 v10, v10
	v_mul_f32_e32 v11, 0x2f800000, v10
	v_floor_f32_e32 v11, v11
	v_fmac_f32_e32 v10, 0xcf800000, v11
	v_cvt_u32_f32_e32 v10, v10
	v_cvt_u32_f32_e32 v11, v11
	global_atomic_add_x2 v180, v[10:11], s[24:25] offset:1408
